# GEMM loops: all 16 LDS-DMA pieces per iteration in saddr form; next-k-step bases kept in two spare SGPR pairs (4 SALU adds) instead of 8 more VALU 64-bit adds
# speedup vs baseline: 1.0444x; 1.0052x over previous
; #define PG8_STAGE(bufoff, gbase, voff) do { _Pragma("unroll") for (int _i = 0; _i < 2; ++_i) \
;         __builtin_amdgcn_global_load_lds((const unsigned*)((const char*)(gbase) + (voff)[_i]), (LAS unsigned*)(lds + (bufoff) + ldsw + _i * 8192), 16, 0, 0); } while (0)
; #define PG8_LDA(dst, b, h) do { _Pragma("unroll") for (int m = 0; m < 4; ++m) _Pragma("unroll") for (int k = 0; k < 2; ++k) dst[m][k] = *(const LAS bf16x8*)(lds + PG8_SA(b, h) + aoff + m * 2048 + k * 1024); } while (0)
; #define PG8_LDB(dst, b, h) do { _Pragma("unroll") for (int n = 0; n < 2; ++n) _Pragma("unroll") for (int k = 0; k < 2; ++k) dst[n][k] = *(const LAS bf16x8*)(lds + PG8_SB(b, h) + boff + n * 2048 + k * 1024); } while (0)
; #define PG8_MMA(ai, bj, At, Bt) do { __builtin_amdgcn_s_setprio(1); _Pragma("unroll") for (int m = 0; m < 4; ++m) _Pragma("unroll") for (int n = 0; n < 2; ++n) _Pragma("unroll") for (int k = 0; k < 2; ++k) \
;         acc[ai][bj][m][n] = __builtin_amdgcn_mfma_f32_16x16x32_bf16(Bt[n][k], At[m][k], acc[ai][bj][m][n], 0, 0, 0); __builtin_amdgcn_s_setprio(0); } while (0)
; #define PG8_WAIT_L(n) asm volatile("s_waitcnt lgkmcnt(" #n ")" ::: "memory")
; #define PG8_BAR __builtin_amdgcn_s_barrier()
; #define PG8_SCHED __builtin_amdgcn_sched_barrier(0)
; template <class Epi>
; __device__ __forceinline__ void gemm_phase(LAS unsigned char* lds, const Gemm g, const StaticOrder& S, const Epi& E) {
;     ...
;         for (int t = 0; t < nt; t += 2) {
;             const bool last = (t == nt - 2);
;             const char* a1 = cA + (size_t)(t + 1) * kstep;
;             const char* a2 = last ? nA : cA + (size_t)(t + 2) * kstep; const char* b2 = last ? nB : cB + (size_t)(t + 2) * kstep;
;             const char* a3 = a2 + kstep; const char* b3 = b2 + kstep;
;             PG8_LDB(B0, 0, 0); PG8_SCHED; PG8_LDA(At, 0, 0); PG8_STAGE(PG8_SA(1, 1), a1 + hstep, voffA);
;             PG8_WAIT_L(8); PG8_BAR; PG8_WAIT_L(0); PG8_MMA(0, 0, At, B0); PG8_BAR; PG8_SCHED;
;             PG8_LDB(B1, 0, 1); PG8_STAGE(PG8_SB(0, 0), b2, voffB);
;             PG8_BAR; PG8_WAIT_L(0); PG8_MMA(0, 1, At, B1); PG8_BAR;
;             PG8_LDA(At, 0, 1); PG8_STAGE(PG8_SA(0, 0), a2, voffA);
;             PG8_BAR; PG8_WAIT_L(0); PG8_MMA(1, 0, At, B0); PG8_BAR; PG8_SCHED;
;             PG8_STAGE(PG8_SB(0, 1), b2 + hstep, voffB);
.LBB0_43:
	s_add_u32 s24, s22, 0xfffc0080
	s_addc_u32 s25, s23, -1
	s_add_i32 s47, 0, 0x10000
	v_add_u32_e32 v140, s47, v247
	ds_read_b128 v[128:131], v140
	ds_read_b128 v[132:135], v140 offset:1024
	ds_read_b128 v[136:139], v140 offset:2048
	ds_read_b128 v[140:143], v140 offset:3072
	s_cmp_eq_u32 s46, 12
	s_cselect_b32 s27, s3, s25
	s_cselect_b32 s26, s9, s24
	s_cselect_b32 s25, s13, s45
	s_cselect_b32 s24, s15, s43
	s_add_i32 m0, s21, 0xc000
	ds_read_b128 v[144:147], v249
	ds_read_b128 v[148:151], v249 offset:1024
	ds_read_b128 v[152:155], v249 offset:2048
	ds_read_b128 v[156:159], v249 offset:3072
	ds_read_b128 v[160:163], v249 offset:4096
	ds_read_b128 v[164:167], v249 offset:5120
	ds_read_b128 v[168:171], v249 offset:6144
	ds_read_b128 v[172:175], v249 offset:7168
	global_load_lds_dwordx4 v214, s[22:23]
	s_add_i32 m0, s21, 0xe000
	s_nop 0
	global_load_lds_dwordx4 v216, s[22:23]
	s_waitcnt lgkmcnt(8)
	s_barrier
	s_waitcnt lgkmcnt(0)
	s_waitcnt lgkmcnt(0)
	v_mfma_f32_16x16x32_bf16 v[124:127], v[128:131], v[144:147], v[124:127]
	v_mfma_f32_16x16x32_bf16 v[124:127], v[132:135], v[148:151], v[124:127]
	v_mfma_f32_16x16x32_bf16 v[108:111], v[128:131], v[152:155], v[108:111]
	v_mfma_f32_16x16x32_bf16 v[108:111], v[132:135], v[156:159], v[108:111]
	v_mfma_f32_16x16x32_bf16 v[92:95], v[128:131], v[160:163], v[92:95]
	v_mfma_f32_16x16x32_bf16 v[92:95], v[132:135], v[164:167], v[92:95]
	v_mfma_f32_16x16x32_bf16 v[76:79], v[128:131], v[168:171], v[76:79]
	v_mfma_f32_16x16x32_bf16 v[76:79], v[132:135], v[172:175], v[76:79]
	v_mfma_f32_16x16x32_bf16 v[72:75], v[136:139], v[168:171], v[72:75]
	v_mfma_f32_16x16x32_bf16 v[72:75], v[140:143], v[172:175], v[72:75]
	v_mfma_f32_16x16x32_bf16 v[88:91], v[136:139], v[160:163], v[88:91]
	v_mfma_f32_16x16x32_bf16 v[88:91], v[140:143], v[164:167], v[88:91]
	v_mfma_f32_16x16x32_bf16 v[104:107], v[136:139], v[152:155], v[104:107]
	v_mfma_f32_16x16x32_bf16 v[104:107], v[140:143], v[156:159], v[104:107]
	v_mfma_f32_16x16x32_bf16 v[120:123], v[136:139], v[144:147], v[120:123]
	v_mfma_f32_16x16x32_bf16 v[120:123], v[140:143], v[148:151], v[120:123]
	s_barrier
	s_add_i32 s52, 0, 0x14000
	v_add_u32_e32 v188, s52, v247
	s_add_i32 s47, s47, s36
	ds_read_b128 v[176:179], v188
	ds_read_b128 v[180:183], v188 offset:1024
	ds_read_b128 v[204:207], v188 offset:2048
	ds_read_b128 v[218:221], v188 offset:3072
	s_mov_b32 m0, s47
	s_add_u32 s98, s24, s58
	s_addc_u32 s99, s25, s59
	global_load_lds_dwordx4 v184, s[24:25]
	s_add_i32 m0, s47, 0x2000
	s_nop 0
	global_load_lds_dwordx4 v212, s[24:25]
	s_barrier
	s_waitcnt lgkmcnt(0)
	s_waitcnt lgkmcnt(0)
	v_mfma_f32_16x16x32_bf16 v[116:119], v[176:179], v[144:147], v[116:119]
	v_mfma_f32_16x16x32_bf16 v[116:119], v[180:183], v[148:151], v[116:119]
	v_mfma_f32_16x16x32_bf16 v[100:103], v[176:179], v[152:155], v[100:103]
	v_mfma_f32_16x16x32_bf16 v[100:103], v[180:183], v[156:159], v[100:103]
	v_mfma_f32_16x16x32_bf16 v[84:87], v[176:179], v[160:163], v[84:87]
	v_mfma_f32_16x16x32_bf16 v[84:87], v[180:183], v[164:167], v[84:87]
	v_mfma_f32_16x16x32_bf16 v[68:71], v[176:179], v[168:171], v[68:71]
	v_mfma_f32_16x16x32_bf16 v[68:71], v[180:183], v[172:175], v[68:71]
	v_mfma_f32_16x16x32_bf16 v[64:67], v[204:207], v[168:171], v[64:67]
	v_mfma_f32_16x16x32_bf16 v[64:67], v[218:221], v[172:175], v[64:67]
	v_mfma_f32_16x16x32_bf16 v[80:83], v[204:207], v[160:163], v[80:83]
	v_mfma_f32_16x16x32_bf16 v[80:83], v[218:221], v[164:167], v[80:83]
	v_mfma_f32_16x16x32_bf16 v[96:99], v[204:207], v[152:155], v[96:99]
	v_mfma_f32_16x16x32_bf16 v[96:99], v[218:221], v[156:159], v[96:99]
	v_mfma_f32_16x16x32_bf16 v[112:115], v[204:207], v[144:147], v[112:115]
	v_mfma_f32_16x16x32_bf16 v[112:115], v[218:221], v[148:151], v[112:115]
	s_mov_b32 m0, s21
	s_barrier
	ds_read_b128 v[144:147], v249 offset:16384
	ds_read_b128 v[148:151], v249 offset:17408
	ds_read_b128 v[152:155], v249 offset:18432
	ds_read_b128 v[156:159], v249 offset:19456
	ds_read_b128 v[160:163], v249 offset:20480
	ds_read_b128 v[164:167], v249 offset:21504
	ds_read_b128 v[168:171], v249 offset:22528
	ds_read_b128 v[172:175], v249 offset:23552
	global_load_lds_dwordx4 v208, s[26:27]
	s_add_u32 s100, s26, s58
	s_addc_u32 s101, s27, s59
	s_mov_b32 m0, s37
	s_nop 0
	global_load_lds_dwordx4 v210, s[26:27]
	s_barrier
	s_waitcnt lgkmcnt(0)
	s_waitcnt lgkmcnt(0)
	v_mfma_f32_16x16x32_bf16 v[60:63], v[128:131], v[144:147], v[60:63]
	v_mfma_f32_16x16x32_bf16 v[60:63], v[132:135], v[148:151], v[60:63]
	v_mfma_f32_16x16x32_bf16 v[44:47], v[128:131], v[152:155], v[44:47]
	v_mfma_f32_16x16x32_bf16 v[44:47], v[132:135], v[156:159], v[44:47]
	v_mfma_f32_16x16x32_bf16 v[28:31], v[128:131], v[160:163], v[28:31]
	v_mfma_f32_16x16x32_bf16 v[28:31], v[132:135], v[164:167], v[28:31]
	v_mfma_f32_16x16x32_bf16 v[16:19], v[128:131], v[168:171], v[16:19]
	v_mfma_f32_16x16x32_bf16 v[16:19], v[132:135], v[172:175], v[16:19]
	v_mfma_f32_16x16x32_bf16 v[8:11], v[136:139], v[168:171], v[8:11]
	v_mfma_f32_16x16x32_bf16 v[8:11], v[140:143], v[172:175], v[8:11]
	v_mfma_f32_16x16x32_bf16 v[24:27], v[136:139], v[160:163], v[24:27]
	v_mfma_f32_16x16x32_bf16 v[24:27], v[140:143], v[164:167], v[24:27]
	v_mfma_f32_16x16x32_bf16 v[40:43], v[136:139], v[152:155], v[40:43]
	v_mfma_f32_16x16x32_bf16 v[40:43], v[140:143], v[156:159], v[40:43]
	v_mfma_f32_16x16x32_bf16 v[56:59], v[136:139], v[144:147], v[56:59]
	v_mfma_f32_16x16x32_bf16 v[56:59], v[140:143], v[148:151], v[56:59]
	s_barrier
	s_add_u32 s50, s24, 0x40000
	s_addc_u32 s51, s25, 0
	s_add_i32 s47, s52, s36
	s_mov_b32 m0, s47
	s_nop 0
	global_load_lds_dwordx4 v184, s[50:51]
	s_add_i32 m0, s47, 0x2000
	s_nop 0
	global_load_lds_dwordx4 v212, s[50:51]
	s_waitcnt vmcnt(6)
	s_barrier
; #define PG8_STAGE(bufoff, gbase, voff) do { _Pragma("unroll") for (int _i = 0; _i < 2; ++_i) \
;         __builtin_amdgcn_global_load_lds((const unsigned*)((const char*)(gbase) + (voff)[_i]), (LAS unsigned*)(lds + (bufoff) + ldsw + _i * 8192), 16, 0, 0); } while (0)
; #define PG8_LDA(dst, b, h) do { _Pragma("unroll") for (int m = 0; m < 4; ++m) _Pragma("unroll") for (int k = 0; k < 2; ++k) dst[m][k] = *(const LAS bf16x8*)(lds + PG8_SA(b, h) + aoff + m * 2048 + k * 1024); } while (0)
; #define PG8_LDB(dst, b, h) do { _Pragma("unroll") for (int n = 0; n < 2; ++n) _Pragma("unroll") for (int k = 0; k < 2; ++k) dst[n][k] = *(const LAS bf16x8*)(lds + PG8_SB(b, h) + boff + n * 2048 + k * 1024); } while (0)
; #define PG8_MMA(ai, bj, At, Bt) do { __builtin_amdgcn_s_setprio(1); _Pragma("unroll") for (int m = 0; m < 4; ++m) _Pragma("unroll") for (int n = 0; n < 2; ++n) _Pragma("unroll") for (int k = 0; k < 2; ++k) \
;         acc[ai][bj][m][n] = __builtin_amdgcn_mfma_f32_16x16x32_bf16(Bt[n][k], At[m][k], acc[ai][bj][m][n], 0, 0, 0); __builtin_amdgcn_s_setprio(0); } while (0)
; #define PG8_WAIT_V(n) asm volatile("s_waitcnt vmcnt(" #n ")" ::: "memory")
; #define PG8_WAIT_L(n) asm volatile("s_waitcnt lgkmcnt(" #n ")" ::: "memory")
; #define PG8_BAR __builtin_amdgcn_s_barrier()
; #define PG8_SCHED __builtin_amdgcn_sched_barrier(0)
; template <class Epi>
; __device__ __forceinline__ void gemm_phase(LAS unsigned char* lds, const Gemm g, const StaticOrder& S, const Epi& E) {
;     ...
;             PG8_WAIT_V(6); PG8_BAR; PG8_MMA(1, 1, At, B1); PG8_BAR;
;             PG8_LDB(B0, 1, 0); PG8_SCHED; PG8_LDA(At, 1, 0); PG8_STAGE(PG8_SA(0, 1), a2 + hstep, voffA);
;             PG8_WAIT_L(8); PG8_BAR; PG8_WAIT_L(0); PG8_MMA(0, 0, At, B0); PG8_BAR; PG8_SCHED;
;             PG8_LDB(B1, 1, 1); PG8_STAGE(PG8_SB(1, 0), b3, voffB);
;             PG8_BAR; PG8_WAIT_L(0); PG8_MMA(0, 1, At, B1); PG8_BAR;
	v_mfma_f32_16x16x32_bf16 v[52:55], v[176:179], v[144:147], v[52:55]
	v_mfma_f32_16x16x32_bf16 v[52:55], v[180:183], v[148:151], v[52:55]
	v_mfma_f32_16x16x32_bf16 v[36:39], v[176:179], v[152:155], v[36:39]
	v_mfma_f32_16x16x32_bf16 v[36:39], v[180:183], v[156:159], v[36:39]
	v_mfma_f32_16x16x32_bf16 v[20:23], v[176:179], v[160:163], v[20:23]
	v_mfma_f32_16x16x32_bf16 v[20:23], v[180:183], v[164:167], v[20:23]
	v_mfma_f32_16x16x32_bf16 v[4:7], v[176:179], v[168:171], v[4:7]
	v_mfma_f32_16x16x32_bf16 v[4:7], v[180:183], v[172:175], v[4:7]
	v_mfma_f32_16x16x32_bf16 v[0:3], v[204:207], v[168:171], v[0:3]
	v_mfma_f32_16x16x32_bf16 v[0:3], v[218:221], v[172:175], v[0:3]
	v_mfma_f32_16x16x32_bf16 v[12:15], v[204:207], v[160:163], v[12:15]
	v_mfma_f32_16x16x32_bf16 v[12:15], v[218:221], v[164:167], v[12:15]
	v_mfma_f32_16x16x32_bf16 v[32:35], v[204:207], v[152:155], v[32:35]
	v_mfma_f32_16x16x32_bf16 v[32:35], v[218:221], v[156:159], v[32:35]
	v_mfma_f32_16x16x32_bf16 v[48:51], v[204:207], v[144:147], v[48:51]
	v_mfma_f32_16x16x32_bf16 v[48:51], v[218:221], v[148:151], v[48:51]
	s_add_i32 s47, 0, 0x18000
	v_add_u32_e32 v140, s47, v247
	s_barrier
	ds_read_b128 v[128:131], v140
	ds_read_b128 v[132:135], v140 offset:1024
	ds_read_b128 v[136:139], v140 offset:2048
	ds_read_b128 v[140:143], v140 offset:3072
	s_add_u32 s26, s26, 0x40000
	s_addc_u32 s27, s27, 0
	s_mov_b32 m0, s38
	ds_read_b128 v[144:147], v249 offset:32768
	ds_read_b128 v[148:151], v249 offset:33792
	ds_read_b128 v[152:155], v249 offset:34816
	ds_read_b128 v[156:159], v249 offset:35840
	ds_read_b128 v[160:163], v249 offset:36864
	ds_read_b128 v[164:167], v249 offset:37888
	ds_read_b128 v[168:171], v249 offset:38912
	ds_read_b128 v[172:175], v249 offset:39936
	global_load_lds_dwordx4 v208, s[26:27]
	s_mov_b32 m0, s39
	s_nop 0
	global_load_lds_dwordx4 v210, s[26:27]
	s_waitcnt lgkmcnt(8)
	s_barrier
	s_waitcnt lgkmcnt(0)
	s_waitcnt lgkmcnt(0)
	v_mfma_f32_16x16x32_bf16 v[124:127], v[128:131], v[144:147], v[124:127]
	v_mfma_f32_16x16x32_bf16 v[124:127], v[132:135], v[148:151], v[124:127]
	v_mfma_f32_16x16x32_bf16 v[108:111], v[128:131], v[152:155], v[108:111]
	v_mfma_f32_16x16x32_bf16 v[108:111], v[132:135], v[156:159], v[108:111]
	v_mfma_f32_16x16x32_bf16 v[92:95], v[128:131], v[160:163], v[92:95]
	v_mfma_f32_16x16x32_bf16 v[92:95], v[132:135], v[164:167], v[92:95]
	v_mfma_f32_16x16x32_bf16 v[76:79], v[128:131], v[168:171], v[76:79]
	v_mfma_f32_16x16x32_bf16 v[76:79], v[132:135], v[172:175], v[76:79]
	v_mfma_f32_16x16x32_bf16 v[72:75], v[136:139], v[168:171], v[72:75]
	v_mfma_f32_16x16x32_bf16 v[72:75], v[140:143], v[172:175], v[72:75]
	v_mfma_f32_16x16x32_bf16 v[88:91], v[136:139], v[160:163], v[88:91]
	v_mfma_f32_16x16x32_bf16 v[88:91], v[140:143], v[164:167], v[88:91]
	v_mfma_f32_16x16x32_bf16 v[104:107], v[136:139], v[152:155], v[104:107]
	v_mfma_f32_16x16x32_bf16 v[104:107], v[140:143], v[156:159], v[104:107]
	v_mfma_f32_16x16x32_bf16 v[120:123], v[136:139], v[144:147], v[120:123]
	v_mfma_f32_16x16x32_bf16 v[120:123], v[140:143], v[148:151], v[120:123]
	s_barrier
	s_add_i32 s26, 0, 0x1c000
	s_add_i32 s27, s47, s36
	v_add_u32_e32 v218, s26, v247
	s_mov_b32 m0, s27
	ds_read_b128 v[176:179], v218
	ds_read_b128 v[180:183], v218 offset:1024
	ds_read_b128 v[204:207], v218 offset:2048
	ds_read_b128 v[218:221], v218 offset:3072
	global_load_lds_dwordx4 v184, s[98:99]
	s_add_i32 m0, s27, 0x2000
	s_nop 0
	global_load_lds_dwordx4 v212, s[98:99]
	s_barrier
	s_waitcnt lgkmcnt(0)
	s_waitcnt lgkmcnt(0)
	v_mfma_f32_16x16x32_bf16 v[116:119], v[176:179], v[144:147], v[116:119]
	v_mfma_f32_16x16x32_bf16 v[116:119], v[180:183], v[148:151], v[116:119]
	v_mfma_f32_16x16x32_bf16 v[100:103], v[176:179], v[152:155], v[100:103]
	v_mfma_f32_16x16x32_bf16 v[100:103], v[180:183], v[156:159], v[100:103]
	v_mfma_f32_16x16x32_bf16 v[84:87], v[176:179], v[160:163], v[84:87]
	v_mfma_f32_16x16x32_bf16 v[84:87], v[180:183], v[164:167], v[84:87]
	v_mfma_f32_16x16x32_bf16 v[68:71], v[176:179], v[168:171], v[68:71]
	v_mfma_f32_16x16x32_bf16 v[68:71], v[180:183], v[172:175], v[68:71]
	v_mfma_f32_16x16x32_bf16 v[64:67], v[204:207], v[168:171], v[64:67]
	v_mfma_f32_16x16x32_bf16 v[64:67], v[218:221], v[172:175], v[64:67]
	v_mfma_f32_16x16x32_bf16 v[80:83], v[204:207], v[160:163], v[80:83]
	v_mfma_f32_16x16x32_bf16 v[80:83], v[218:221], v[164:167], v[80:83]
	v_mfma_f32_16x16x32_bf16 v[96:99], v[204:207], v[152:155], v[96:99]
	v_mfma_f32_16x16x32_bf16 v[96:99], v[218:221], v[156:159], v[96:99]
	v_mfma_f32_16x16x32_bf16 v[112:115], v[204:207], v[144:147], v[112:115]
	v_mfma_f32_16x16x32_bf16 v[112:115], v[218:221], v[148:151], v[112:115]
	s_mov_b32 m0, s41
	s_barrier
; #define PG8_STAGE(bufoff, gbase, voff) do { _Pragma("unroll") for (int _i = 0; _i < 2; ++_i) \
;         __builtin_amdgcn_global_load_lds((const unsigned*)((const char*)(gbase) + (voff)[_i]), (LAS unsigned*)(lds + (bufoff) + ldsw + _i * 8192), 16, 0, 0); } while (0)
; #define PG8_LDA(dst, b, h) do { _Pragma("unroll") for (int m = 0; m < 4; ++m) _Pragma("unroll") for (int k = 0; k < 2; ++k) dst[m][k] = *(const LAS bf16x8*)(lds + PG8_SA(b, h) + aoff + m * 2048 + k * 1024); } while (0)
; #define PG8_MMA(ai, bj, At, Bt) do { __builtin_amdgcn_s_setprio(1); _Pragma("unroll") for (int m = 0; m < 4; ++m) _Pragma("unroll") for (int n = 0; n < 2; ++n) _Pragma("unroll") for (int k = 0; k < 2; ++k) \
;         acc[ai][bj][m][n] = __builtin_amdgcn_mfma_f32_16x16x32_bf16(Bt[n][k], At[m][k], acc[ai][bj][m][n], 0, 0, 0); __builtin_amdgcn_s_setprio(0); } while (0)
; #define PG8_WAIT_V(n) asm volatile("s_waitcnt vmcnt(" #n ")" ::: "memory")
; #define PG8_WAIT_L(n) asm volatile("s_waitcnt lgkmcnt(" #n ")" ::: "memory")
; #define PG8_BAR __builtin_amdgcn_s_barrier()
; #define PG8_SCHED __builtin_amdgcn_sched_barrier(0)
; template <class Epi>
; __device__ __forceinline__ void gemm_phase(LAS unsigned char* lds, const Gemm g, const StaticOrder& S, const Epi& E) {
;     ...
;             PG8_LDA(At, 1, 1); PG8_STAGE(PG8_SA(1, 0), a3, voffA);
;             PG8_BAR; PG8_WAIT_L(0); PG8_MMA(1, 0, At, B0); PG8_BAR; PG8_SCHED;
;             PG8_STAGE(PG8_SB(1, 1), b3 + hstep, voffB);
;             PG8_WAIT_V(6); PG8_BAR; PG8_MMA(1, 1, At, B1); PG8_BAR;
;     __device__ __forceinline__ void operator()(const Acc& acc, const Unit& u, int wr, int wc, int fr, int fq) const {
;         const int row0 = u.pm * 256 + wr * 64 + fr, col0 = u.pn * 256 + wc * 32 + 8 * fq;
;         const bf16_t* __restrict__ gp = gate; bf16_t* __restrict__ mg = merged;
;         u32x4 gw[4][2], pw[2][2];
; #pragma unroll
;         for (int gidx = 0; gidx < 4; ++gidx)
; #pragma unroll
;             for (int bj = 0; bj < 2; ++bj) gw[gidx][bj] = *(const u32x4*)(gp + (size_t)(row0 + gidx * 16) * 4096 + col0 + bj * 128);
; #pragma unroll
;         for (int bj = 0; bj < 2; ++bj) pw[0][bj] = accum ? *(const u32x4*)(mg + (size_t)row0 * 2048 + col0 + bj * 128) : (u32x4){0u, 0u, 0u, 0u};
	ds_read_b128 v[144:147], v249 offset:49152
	ds_read_b128 v[148:151], v249 offset:50176
	ds_read_b128 v[152:155], v249 offset:51200
	ds_read_b128 v[156:159], v249 offset:52224
	ds_read_b128 v[160:163], v249 offset:53248
	ds_read_b128 v[164:167], v249 offset:54272
	ds_read_b128 v[168:171], v249 offset:55296
	ds_read_b128 v[172:175], v249 offset:56320
	global_load_lds_dwordx4 v208, s[100:101]
	s_mov_b32 m0, s42
	s_nop 0
	global_load_lds_dwordx4 v210, s[100:101]
	s_barrier
	s_waitcnt lgkmcnt(0)
	s_waitcnt lgkmcnt(0)
	v_mfma_f32_16x16x32_bf16 v[60:63], v[128:131], v[144:147], v[60:63]
	v_mfma_f32_16x16x32_bf16 v[60:63], v[132:135], v[148:151], v[60:63]
	v_mfma_f32_16x16x32_bf16 v[44:47], v[128:131], v[152:155], v[44:47]
	v_mfma_f32_16x16x32_bf16 v[44:47], v[132:135], v[156:159], v[44:47]
	v_mfma_f32_16x16x32_bf16 v[28:31], v[128:131], v[160:163], v[28:31]
	v_mfma_f32_16x16x32_bf16 v[28:31], v[132:135], v[164:167], v[28:31]
	v_mfma_f32_16x16x32_bf16 v[16:19], v[128:131], v[168:171], v[16:19]
	v_mfma_f32_16x16x32_bf16 v[16:19], v[132:135], v[172:175], v[16:19]
	v_mfma_f32_16x16x32_bf16 v[8:11], v[136:139], v[168:171], v[8:11]
	v_mfma_f32_16x16x32_bf16 v[8:11], v[140:143], v[172:175], v[8:11]
	v_mfma_f32_16x16x32_bf16 v[24:27], v[136:139], v[160:163], v[24:27]
	v_mfma_f32_16x16x32_bf16 v[24:27], v[140:143], v[164:167], v[24:27]
	v_mfma_f32_16x16x32_bf16 v[40:43], v[136:139], v[152:155], v[40:43]
	v_mfma_f32_16x16x32_bf16 v[40:43], v[140:143], v[156:159], v[40:43]
	v_mfma_f32_16x16x32_bf16 v[56:59], v[136:139], v[144:147], v[56:59]
	v_mfma_f32_16x16x32_bf16 v[56:59], v[140:143], v[148:151], v[56:59]
	s_barrier
	s_add_u32 s24, s24, 0x40080
	s_addc_u32 s25, s25, 0
	s_add_i32 s26, s26, s36
	s_mov_b32 m0, s26
	s_nop 0
	global_load_lds_dwordx4 v184, s[24:25]
	s_add_i32 m0, s26, 0x2000
	s_nop 0
	global_load_lds_dwordx4 v212, s[24:25]
	s_waitcnt vmcnt(6)
	s_barrier
	v_mfma_f32_16x16x32_bf16 v[52:55], v[176:179], v[144:147], v[52:55]
	v_mfma_f32_16x16x32_bf16 v[52:55], v[180:183], v[148:151], v[52:55]
	v_mfma_f32_16x16x32_bf16 v[36:39], v[176:179], v[152:155], v[36:39]
	v_mfma_f32_16x16x32_bf16 v[36:39], v[180:183], v[156:159], v[36:39]
	v_mfma_f32_16x16x32_bf16 v[20:23], v[176:179], v[160:163], v[20:23]
	v_mfma_f32_16x16x32_bf16 v[20:23], v[180:183], v[164:167], v[20:23]
	v_mfma_f32_16x16x32_bf16 v[4:7], v[176:179], v[168:171], v[4:7]
	v_mfma_f32_16x16x32_bf16 v[4:7], v[180:183], v[172:175], v[4:7]
	v_mfma_f32_16x16x32_bf16 v[0:3], v[204:207], v[168:171], v[0:3]
	v_mfma_f32_16x16x32_bf16 v[0:3], v[218:221], v[172:175], v[0:3]
	v_mfma_f32_16x16x32_bf16 v[12:15], v[204:207], v[160:163], v[12:15]
	v_mfma_f32_16x16x32_bf16 v[12:15], v[218:221], v[164:167], v[12:15]
	v_mfma_f32_16x16x32_bf16 v[32:35], v[204:207], v[152:155], v[32:35]
	v_mfma_f32_16x16x32_bf16 v[32:35], v[218:221], v[156:159], v[32:35]
	v_mfma_f32_16x16x32_bf16 v[48:51], v[204:207], v[144:147], v[48:51]
	v_mfma_f32_16x16x32_bf16 v[48:51], v[218:221], v[148:151], v[48:51]
	s_add_i32 s46, s46, 2
	s_add_u32 s22, s22, 0x100
	s_addc_u32 s23, s23, 0
	s_add_u32 s43, s43, 0x100
	s_addc_u32 s45, s45, 0
	s_cmp_gt_u32 s46, 13
	s_barrier
	s_cbranch_scc0 .LBB0_43
	v_lshl_or_b32 v128, s8, 8, v248
	v_lshl_add_u32 v222, s20, 8, v187
	v_ashrrev_i32_e32 v129, 31, v128
	v_lshlrev_b64 v[136:137], 1, v[128:129]
	v_ashrrev_i32_e32 v223, 31, v222
	v_lshl_add_u64 v[224:225], s[10:11], 0, v[136:137]
	v_lshlrev_b64 v[130:131], 13, v[222:223]
	v_lshl_add_u64 v[130:131], v[224:225], 0, v[130:131]
	global_load_dwordx4 v[176:179], v[130:131], off
	global_load_dwordx4 v[168:171], v[130:131], off offset:256
	v_or_b32_e32 v130, 16, v222
	v_ashrrev_i32_e32 v131, 31, v130
	v_lshlrev_b64 v[132:133], 13, v[130:131]
	v_or_b32_e32 v230, 32, v222
	v_lshl_add_u64 v[132:133], v[224:225], 0, v[132:133]
	v_ashrrev_i32_e32 v231, 31, v230
	global_load_dwordx4 v[156:159], v[132:133], off
	global_load_dwordx4 v[152:155], v[132:133], off offset:256
	v_lshlrev_b64 v[132:133], 13, v[230:231]
	v_or_b32_e32 v226, 48, v222
	v_lshl_add_u64 v[132:133], v[224:225], 0, v[132:133]
	v_ashrrev_i32_e32 v227, 31, v226
	global_load_dwordx4 v[148:151], v[132:133], off
	global_load_dwordx4 v[144:147], v[132:133], off offset:256
	v_lshlrev_b64 v[132:133], 13, v[226:227]
	v_lshl_add_u64 v[132:133], v[224:225], 0, v[132:133]
	global_load_dwordx4 v[140:143], v[132:133], off
	s_nop 0
	global_load_dwordx4 v[132:135], v[132:133], off offset:256
	v_lshlrev_b64 v[232:233], 12, v[222:223]
	v_lshl_add_u64 v[138:139], s[66:67], 0, v[232:233]
	v_lshl_add_u64 v[136:137], v[138:139], 0, v[136:137]
	v_cndmask_b32_e64 v138, 0, 1, s[0:1]
	v_mov_b32_e32 v172, 0
	v_cmp_ne_u32_e64 s[8:9], 1, v138
	s_andn2_b64 vcc, exec, s[0:1]
	v_mov_b32_e32 v180, 0
	v_mov_b32_e32 v181, 0
	v_mov_b32_e32 v182, 0
	v_mov_b32_e32 v183, 0
	s_cbranch_vccnz .LBB0_46
	global_load_dwordx4 v[180:183], v[136:137], off

; #define PG8_STAGE(bufoff, gbase, voff) do { _Pragma("unroll") for (int _i = 0; _i < 2; ++_i) \
;         __builtin_amdgcn_global_load_lds((const unsigned*)((const char*)(gbase) + (voff)[_i]), (LAS unsigned*)(lds + (bufoff) + ldsw + _i * 8192), 16, 0, 0); } while (0)
; #define PG8_LDA(dst, b, h) do { _Pragma("unroll") for (int m = 0; m < 4; ++m) _Pragma("unroll") for (int k = 0; k < 2; ++k) dst[m][k] = *(const LAS bf16x8*)(lds + PG8_SA(b, h) + aoff + m * 2048 + k * 1024); } while (0)
; #define PG8_LDB(dst, b, h) do { _Pragma("unroll") for (int n = 0; n < 2; ++n) _Pragma("unroll") for (int k = 0; k < 2; ++k) dst[n][k] = *(const LAS bf16x8*)(lds + PG8_SB(b, h) + boff + n * 2048 + k * 1024); } while (0)
; #define PG8_MMA(ai, bj, At, Bt) do { __builtin_amdgcn_s_setprio(1); _Pragma("unroll") for (int m = 0; m < 4; ++m) _Pragma("unroll") for (int n = 0; n < 2; ++n) _Pragma("unroll") for (int k = 0; k < 2; ++k) \
;         acc[ai][bj][m][n] = __builtin_amdgcn_mfma_f32_16x16x32_bf16(Bt[n][k], At[m][k], acc[ai][bj][m][n], 0, 0, 0); __builtin_amdgcn_s_setprio(0); } while (0)
; #define PG8_WAIT_L(n) asm volatile("s_waitcnt lgkmcnt(" #n ")" ::: "memory")
; #define PG8_BAR __builtin_amdgcn_s_barrier()
; #define PG8_SCHED __builtin_amdgcn_sched_barrier(0)
; template <class Epi>
; __device__ __forceinline__ void gemm_phase(LAS unsigned char* lds, const Gemm g, const StaticOrder& S, const Epi& E) {
;     ...
;         for (int t = 0; t < nt; t += 2) {
;             const bool last = (t == nt - 2);
;             const char* a1 = cA + (size_t)(t + 1) * kstep;
;             const char* a2 = last ? nA : cA + (size_t)(t + 2) * kstep; const char* b2 = last ? nB : cB + (size_t)(t + 2) * kstep;
;             const char* a3 = a2 + kstep; const char* b3 = b2 + kstep;
;             PG8_LDB(B0, 0, 0); PG8_SCHED; PG8_LDA(At, 0, 0); PG8_STAGE(PG8_SA(1, 1), a1 + hstep, voffA);
;             PG8_WAIT_L(8); PG8_BAR; PG8_WAIT_L(0); PG8_MMA(0, 0, At, B0); PG8_BAR; PG8_SCHED;
;             PG8_LDB(B1, 0, 1); PG8_STAGE(PG8_SB(0, 0), b2, voffB);
;             PG8_BAR; PG8_WAIT_L(0); PG8_MMA(0, 1, At, B1); PG8_BAR;
;             PG8_LDA(At, 0, 1); PG8_STAGE(PG8_SA(0, 0), a2, voffA);
;             PG8_BAR; PG8_WAIT_L(0); PG8_MMA(1, 0, At, B0); PG8_BAR; PG8_SCHED;
;             PG8_STAGE(PG8_SB(0, 1), b2 + hstep, voffB);
.LBB0_366:
	s_add_u32 s28, s26, 0xfff80080
	s_addc_u32 s29, s27, -1
	s_add_i32 s47, 0, 0x10000
	v_add_u32_e32 v154, s47, v143
	ds_read_b128 v[138:141], v154
	ds_read_b128 v[146:149], v154 offset:1024
	ds_read_b128 v[150:153], v154 offset:2048
	ds_read_b128 v[154:157], v154 offset:3072
	s_cmp_eq_u32 s43, 28
	s_cselect_b32 s31, s3, s29
	s_cselect_b32 s30, s9, s28
	s_cselect_b32 s29, s1, s35
	s_cselect_b32 s28, s19, s34
	s_add_i32 m0, s25, 0xc000
	ds_read_b128 v[158:161], v145
	ds_read_b128 v[162:165], v145 offset:1024
	ds_read_b128 v[166:169], v145 offset:2048
	ds_read_b128 v[170:173], v145 offset:3072
	ds_read_b128 v[174:177], v145 offset:4096
	ds_read_b128 v[178:181], v145 offset:5120
	ds_read_b128 v[204:207], v145 offset:6144
	ds_read_b128 v[208:211], v145 offset:7168
	global_load_lds_dwordx4 v134, s[26:27]
	s_add_i32 m0, s25, 0xe000
	s_nop 0
	global_load_lds_dwordx4 v136, s[26:27]
	s_waitcnt lgkmcnt(8)
	s_barrier
	s_waitcnt lgkmcnt(0)
	s_waitcnt lgkmcnt(0)
	v_mfma_f32_16x16x32_bf16 v[124:127], v[138:141], v[158:161], v[124:127]
	v_mfma_f32_16x16x32_bf16 v[124:127], v[146:149], v[162:165], v[124:127]
	v_mfma_f32_16x16x32_bf16 v[108:111], v[138:141], v[166:169], v[108:111]
	v_mfma_f32_16x16x32_bf16 v[108:111], v[146:149], v[170:173], v[108:111]
	v_mfma_f32_16x16x32_bf16 v[92:95], v[138:141], v[174:177], v[92:95]
	v_mfma_f32_16x16x32_bf16 v[92:95], v[146:149], v[178:181], v[92:95]
	v_mfma_f32_16x16x32_bf16 v[76:79], v[138:141], v[204:207], v[76:79]
	v_mfma_f32_16x16x32_bf16 v[76:79], v[146:149], v[208:211], v[76:79]
	v_mfma_f32_16x16x32_bf16 v[72:75], v[150:153], v[204:207], v[72:75]
	v_mfma_f32_16x16x32_bf16 v[72:75], v[154:157], v[208:211], v[72:75]
	v_mfma_f32_16x16x32_bf16 v[88:91], v[150:153], v[174:177], v[88:91]
	v_mfma_f32_16x16x32_bf16 v[88:91], v[154:157], v[178:181], v[88:91]
	v_mfma_f32_16x16x32_bf16 v[104:107], v[150:153], v[166:169], v[104:107]
	v_mfma_f32_16x16x32_bf16 v[104:107], v[154:157], v[170:173], v[104:107]
	v_mfma_f32_16x16x32_bf16 v[120:123], v[150:153], v[158:161], v[120:123]
	v_mfma_f32_16x16x32_bf16 v[120:123], v[154:157], v[162:165], v[120:123]
	s_barrier
	s_add_i32 s52, 0, 0x14000
	v_add_u32_e32 v182, s52, v143
	s_add_i32 s47, s47, s38
	ds_read_b128 v[212:215], v182
	ds_read_b128 v[216:219], v182 offset:1024
	ds_read_b128 v[220:223], v182 offset:2048
	ds_read_b128 v[224:227], v182 offset:3072
	s_mov_b32 m0, s47
	s_add_u32 s98, s28, s58
	s_addc_u32 s99, s29, s59
	global_load_lds_dwordx4 v184, s[28:29]
	s_add_i32 m0, s47, 0x2000
	s_nop 0
	global_load_lds_dwordx4 v132, s[28:29]
	s_barrier
	s_waitcnt lgkmcnt(0)
	s_waitcnt lgkmcnt(0)
	v_mfma_f32_16x16x32_bf16 v[116:119], v[212:215], v[158:161], v[116:119]
	v_mfma_f32_16x16x32_bf16 v[116:119], v[216:219], v[162:165], v[116:119]
	v_mfma_f32_16x16x32_bf16 v[100:103], v[212:215], v[166:169], v[100:103]
	v_mfma_f32_16x16x32_bf16 v[100:103], v[216:219], v[170:173], v[100:103]
	v_mfma_f32_16x16x32_bf16 v[84:87], v[212:215], v[174:177], v[84:87]
	v_mfma_f32_16x16x32_bf16 v[84:87], v[216:219], v[178:181], v[84:87]
	v_mfma_f32_16x16x32_bf16 v[68:71], v[212:215], v[204:207], v[68:71]
	v_mfma_f32_16x16x32_bf16 v[68:71], v[216:219], v[208:211], v[68:71]
	v_mfma_f32_16x16x32_bf16 v[64:67], v[220:223], v[204:207], v[64:67]
	v_mfma_f32_16x16x32_bf16 v[64:67], v[224:227], v[208:211], v[64:67]
	v_mfma_f32_16x16x32_bf16 v[80:83], v[220:223], v[174:177], v[80:83]
	v_mfma_f32_16x16x32_bf16 v[80:83], v[224:227], v[178:181], v[80:83]
	v_mfma_f32_16x16x32_bf16 v[96:99], v[220:223], v[166:169], v[96:99]
	v_mfma_f32_16x16x32_bf16 v[96:99], v[224:227], v[170:173], v[96:99]
	v_mfma_f32_16x16x32_bf16 v[112:115], v[220:223], v[158:161], v[112:115]
	v_mfma_f32_16x16x32_bf16 v[112:115], v[224:227], v[162:165], v[112:115]
	s_mov_b32 m0, s25
	s_barrier
	ds_read_b128 v[158:161], v145 offset:16384
	ds_read_b128 v[162:165], v145 offset:17408
	ds_read_b128 v[166:169], v145 offset:18432
	ds_read_b128 v[170:173], v145 offset:19456
	ds_read_b128 v[174:177], v145 offset:20480
	ds_read_b128 v[178:181], v145 offset:21504
	ds_read_b128 v[204:207], v145 offset:22528
	ds_read_b128 v[208:211], v145 offset:23552
	global_load_lds_dwordx4 v128, s[30:31]
	s_add_u32 s100, s30, s58
	s_addc_u32 s101, s31, s59
	s_mov_b32 m0, s39
	s_nop 0
	global_load_lds_dwordx4 v130, s[30:31]
	s_barrier
	s_waitcnt lgkmcnt(0)
	s_waitcnt lgkmcnt(0)
	v_mfma_f32_16x16x32_bf16 v[60:63], v[138:141], v[158:161], v[60:63]
	v_mfma_f32_16x16x32_bf16 v[60:63], v[146:149], v[162:165], v[60:63]
	v_mfma_f32_16x16x32_bf16 v[44:47], v[138:141], v[166:169], v[44:47]
	v_mfma_f32_16x16x32_bf16 v[44:47], v[146:149], v[170:173], v[44:47]
	v_mfma_f32_16x16x32_bf16 v[28:31], v[138:141], v[174:177], v[28:31]
	v_mfma_f32_16x16x32_bf16 v[28:31], v[146:149], v[178:181], v[28:31]
	v_mfma_f32_16x16x32_bf16 v[12:15], v[138:141], v[204:207], v[12:15]
	v_mfma_f32_16x16x32_bf16 v[12:15], v[146:149], v[208:211], v[12:15]
	v_mfma_f32_16x16x32_bf16 v[8:11], v[150:153], v[204:207], v[8:11]
	v_mfma_f32_16x16x32_bf16 v[8:11], v[154:157], v[208:211], v[8:11]
	v_mfma_f32_16x16x32_bf16 v[24:27], v[150:153], v[174:177], v[24:27]
	v_mfma_f32_16x16x32_bf16 v[24:27], v[154:157], v[178:181], v[24:27]
	v_mfma_f32_16x16x32_bf16 v[40:43], v[150:153], v[166:169], v[40:43]
	v_mfma_f32_16x16x32_bf16 v[40:43], v[154:157], v[170:173], v[40:43]
	v_mfma_f32_16x16x32_bf16 v[56:59], v[150:153], v[158:161], v[56:59]
	v_mfma_f32_16x16x32_bf16 v[56:59], v[154:157], v[162:165], v[56:59]
	s_barrier
	s_add_u32 s50, s28, 0x80000
	s_addc_u32 s51, s29, 0
	s_add_i32 s47, s52, s38
	s_mov_b32 m0, s47
	s_nop 0
	global_load_lds_dwordx4 v184, s[50:51]
	s_add_i32 m0, s47, 0x2000
	s_nop 0
	global_load_lds_dwordx4 v132, s[50:51]
	s_waitcnt vmcnt(6)
	s_barrier
; #define PG8_STAGE(bufoff, gbase, voff) do { _Pragma("unroll") for (int _i = 0; _i < 2; ++_i) \
;         __builtin_amdgcn_global_load_lds((const unsigned*)((const char*)(gbase) + (voff)[_i]), (LAS unsigned*)(lds + (bufoff) + ldsw + _i * 8192), 16, 0, 0); } while (0)
; #define PG8_LDA(dst, b, h) do { _Pragma("unroll") for (int m = 0; m < 4; ++m) _Pragma("unroll") for (int k = 0; k < 2; ++k) dst[m][k] = *(const LAS bf16x8*)(lds + PG8_SA(b, h) + aoff + m * 2048 + k * 1024); } while (0)
; #define PG8_LDB(dst, b, h) do { _Pragma("unroll") for (int n = 0; n < 2; ++n) _Pragma("unroll") for (int k = 0; k < 2; ++k) dst[n][k] = *(const LAS bf16x8*)(lds + PG8_SB(b, h) + boff + n * 2048 + k * 1024); } while (0)
; #define PG8_MMA(ai, bj, At, Bt) do { __builtin_amdgcn_s_setprio(1); _Pragma("unroll") for (int m = 0; m < 4; ++m) _Pragma("unroll") for (int n = 0; n < 2; ++n) _Pragma("unroll") for (int k = 0; k < 2; ++k) \
;         acc[ai][bj][m][n] = __builtin_amdgcn_mfma_f32_16x16x32_bf16(Bt[n][k], At[m][k], acc[ai][bj][m][n], 0, 0, 0); __builtin_amdgcn_s_setprio(0); } while (0)
; #define PG8_WAIT_V(n) asm volatile("s_waitcnt vmcnt(" #n ")" ::: "memory")
; #define PG8_WAIT_L(n) asm volatile("s_waitcnt lgkmcnt(" #n ")" ::: "memory")
; #define PG8_BAR __builtin_amdgcn_s_barrier()
; #define PG8_SCHED __builtin_amdgcn_sched_barrier(0)
; template <class Epi>
; __device__ __forceinline__ void gemm_phase(LAS unsigned char* lds, const Gemm g, const StaticOrder& S, const Epi& E) {
;     ...
;             PG8_WAIT_V(6); PG8_BAR; PG8_MMA(1, 1, At, B1); PG8_BAR;
;             PG8_LDB(B0, 1, 0); PG8_SCHED; PG8_LDA(At, 1, 0); PG8_STAGE(PG8_SA(0, 1), a2 + hstep, voffA);
;             PG8_WAIT_L(8); PG8_BAR; PG8_WAIT_L(0); PG8_MMA(0, 0, At, B0); PG8_BAR; PG8_SCHED;
;             PG8_LDB(B1, 1, 1); PG8_STAGE(PG8_SB(1, 0), b3, voffB);
;             PG8_BAR; PG8_WAIT_L(0); PG8_MMA(0, 1, At, B1); PG8_BAR;
	v_mfma_f32_16x16x32_bf16 v[52:55], v[212:215], v[158:161], v[52:55]
	v_mfma_f32_16x16x32_bf16 v[52:55], v[216:219], v[162:165], v[52:55]
	v_mfma_f32_16x16x32_bf16 v[36:39], v[212:215], v[166:169], v[36:39]
	v_mfma_f32_16x16x32_bf16 v[36:39], v[216:219], v[170:173], v[36:39]
	v_mfma_f32_16x16x32_bf16 v[20:23], v[212:215], v[174:177], v[20:23]
	v_mfma_f32_16x16x32_bf16 v[20:23], v[216:219], v[178:181], v[20:23]
	v_mfma_f32_16x16x32_bf16 v[4:7], v[212:215], v[204:207], v[4:7]
	v_mfma_f32_16x16x32_bf16 v[4:7], v[216:219], v[208:211], v[4:7]
	v_mfma_f32_16x16x32_bf16 v[0:3], v[220:223], v[204:207], v[0:3]
	v_mfma_f32_16x16x32_bf16 v[0:3], v[224:227], v[208:211], v[0:3]
	v_mfma_f32_16x16x32_bf16 v[16:19], v[220:223], v[174:177], v[16:19]
	v_mfma_f32_16x16x32_bf16 v[16:19], v[224:227], v[178:181], v[16:19]
	v_mfma_f32_16x16x32_bf16 v[32:35], v[220:223], v[166:169], v[32:35]
	v_mfma_f32_16x16x32_bf16 v[32:35], v[224:227], v[170:173], v[32:35]
	v_mfma_f32_16x16x32_bf16 v[48:51], v[220:223], v[158:161], v[48:51]
	v_mfma_f32_16x16x32_bf16 v[48:51], v[224:227], v[162:165], v[48:51]
	s_add_i32 s47, 0, 0x18000
	v_add_u32_e32 v154, s47, v143
	s_barrier
	ds_read_b128 v[138:141], v154
	ds_read_b128 v[146:149], v154 offset:1024
	ds_read_b128 v[150:153], v154 offset:2048
	ds_read_b128 v[154:157], v154 offset:3072
	s_add_u32 s30, s30, 0x80000
	s_addc_u32 s31, s31, 0
	s_mov_b32 m0, s40
	ds_read_b128 v[158:161], v145 offset:32768
	ds_read_b128 v[162:165], v145 offset:33792
	ds_read_b128 v[166:169], v145 offset:34816
	ds_read_b128 v[170:173], v145 offset:35840
	ds_read_b128 v[174:177], v145 offset:36864
	ds_read_b128 v[178:181], v145 offset:37888
	ds_read_b128 v[204:207], v145 offset:38912
	ds_read_b128 v[208:211], v145 offset:39936
	global_load_lds_dwordx4 v128, s[30:31]
	s_mov_b32 m0, s41
	s_nop 0
	global_load_lds_dwordx4 v130, s[30:31]
	s_waitcnt lgkmcnt(8)
	s_barrier
	s_waitcnt lgkmcnt(0)
	s_waitcnt lgkmcnt(0)
	v_mfma_f32_16x16x32_bf16 v[124:127], v[138:141], v[158:161], v[124:127]
	v_mfma_f32_16x16x32_bf16 v[124:127], v[146:149], v[162:165], v[124:127]
	v_mfma_f32_16x16x32_bf16 v[108:111], v[138:141], v[166:169], v[108:111]
	v_mfma_f32_16x16x32_bf16 v[108:111], v[146:149], v[170:173], v[108:111]
	v_mfma_f32_16x16x32_bf16 v[92:95], v[138:141], v[174:177], v[92:95]
	v_mfma_f32_16x16x32_bf16 v[92:95], v[146:149], v[178:181], v[92:95]
	v_mfma_f32_16x16x32_bf16 v[76:79], v[138:141], v[204:207], v[76:79]
	v_mfma_f32_16x16x32_bf16 v[76:79], v[146:149], v[208:211], v[76:79]
	v_mfma_f32_16x16x32_bf16 v[72:75], v[150:153], v[204:207], v[72:75]
	v_mfma_f32_16x16x32_bf16 v[72:75], v[154:157], v[208:211], v[72:75]
	v_mfma_f32_16x16x32_bf16 v[88:91], v[150:153], v[174:177], v[88:91]
	v_mfma_f32_16x16x32_bf16 v[88:91], v[154:157], v[178:181], v[88:91]
	v_mfma_f32_16x16x32_bf16 v[104:107], v[150:153], v[166:169], v[104:107]
	v_mfma_f32_16x16x32_bf16 v[104:107], v[154:157], v[170:173], v[104:107]
	v_mfma_f32_16x16x32_bf16 v[120:123], v[150:153], v[158:161], v[120:123]
	v_mfma_f32_16x16x32_bf16 v[120:123], v[154:157], v[162:165], v[120:123]
	s_barrier
	s_add_i32 s30, 0, 0x1c000
	s_add_i32 s31, s47, s38
	v_add_u32_e32 v187, s30, v143
	s_mov_b32 m0, s31
	ds_read_b128 v[212:215], v187
	ds_read_b128 v[216:219], v187 offset:1024
	ds_read_b128 v[220:223], v187 offset:2048
	ds_read_b128 v[224:227], v187 offset:3072
	global_load_lds_dwordx4 v184, s[98:99]
	s_add_i32 m0, s31, 0x2000
	s_nop 0
	global_load_lds_dwordx4 v132, s[98:99]
	s_barrier
	s_waitcnt lgkmcnt(0)
	s_waitcnt lgkmcnt(0)
	v_mfma_f32_16x16x32_bf16 v[116:119], v[212:215], v[158:161], v[116:119]
	v_mfma_f32_16x16x32_bf16 v[116:119], v[216:219], v[162:165], v[116:119]
	v_mfma_f32_16x16x32_bf16 v[100:103], v[212:215], v[166:169], v[100:103]
	v_mfma_f32_16x16x32_bf16 v[100:103], v[216:219], v[170:173], v[100:103]
	v_mfma_f32_16x16x32_bf16 v[84:87], v[212:215], v[174:177], v[84:87]
	v_mfma_f32_16x16x32_bf16 v[84:87], v[216:219], v[178:181], v[84:87]
	v_mfma_f32_16x16x32_bf16 v[68:71], v[212:215], v[204:207], v[68:71]
	v_mfma_f32_16x16x32_bf16 v[68:71], v[216:219], v[208:211], v[68:71]
	v_mfma_f32_16x16x32_bf16 v[64:67], v[220:223], v[204:207], v[64:67]
	v_mfma_f32_16x16x32_bf16 v[64:67], v[224:227], v[208:211], v[64:67]
	v_mfma_f32_16x16x32_bf16 v[80:83], v[220:223], v[174:177], v[80:83]
	v_mfma_f32_16x16x32_bf16 v[80:83], v[224:227], v[178:181], v[80:83]
	v_mfma_f32_16x16x32_bf16 v[96:99], v[220:223], v[166:169], v[96:99]
	v_mfma_f32_16x16x32_bf16 v[96:99], v[224:227], v[170:173], v[96:99]
	v_mfma_f32_16x16x32_bf16 v[112:115], v[220:223], v[158:161], v[112:115]
	v_mfma_f32_16x16x32_bf16 v[112:115], v[224:227], v[162:165], v[112:115]
	s_mov_b32 m0, s42
	s_barrier
; #define PG8_STAGE(bufoff, gbase, voff) do { _Pragma("unroll") for (int _i = 0; _i < 2; ++_i) \
;         __builtin_amdgcn_global_load_lds((const unsigned*)((const char*)(gbase) + (voff)[_i]), (LAS unsigned*)(lds + (bufoff) + ldsw + _i * 8192), 16, 0, 0); } while (0)
; #define PG8_LDA(dst, b, h) do { _Pragma("unroll") for (int m = 0; m < 4; ++m) _Pragma("unroll") for (int k = 0; k < 2; ++k) dst[m][k] = *(const LAS bf16x8*)(lds + PG8_SA(b, h) + aoff + m * 2048 + k * 1024); } while (0)
; #define PG8_MMA(ai, bj, At, Bt) do { __builtin_amdgcn_s_setprio(1); _Pragma("unroll") for (int m = 0; m < 4; ++m) _Pragma("unroll") for (int n = 0; n < 2; ++n) _Pragma("unroll") for (int k = 0; k < 2; ++k) \
;         acc[ai][bj][m][n] = __builtin_amdgcn_mfma_f32_16x16x32_bf16(Bt[n][k], At[m][k], acc[ai][bj][m][n], 0, 0, 0); __builtin_amdgcn_s_setprio(0); } while (0)
; #define PG8_WAIT_V(n) asm volatile("s_waitcnt vmcnt(" #n ")" ::: "memory")
; #define PG8_WAIT_L(n) asm volatile("s_waitcnt lgkmcnt(" #n ")" ::: "memory")
; #define PG8_BAR __builtin_amdgcn_s_barrier()
; #define PG8_SCHED __builtin_amdgcn_sched_barrier(0)
; template <class Epi>
; __device__ __forceinline__ void gemm_phase(LAS unsigned char* lds, const Gemm g, const StaticOrder& S, const Epi& E) {
;     ...
;             PG8_LDA(At, 1, 1); PG8_STAGE(PG8_SA(1, 0), a3, voffA);
;             PG8_BAR; PG8_WAIT_L(0); PG8_MMA(1, 0, At, B0); PG8_BAR; PG8_SCHED;
;             PG8_STAGE(PG8_SB(1, 1), b3 + hstep, voffB);
;             PG8_WAIT_V(6); PG8_BAR; PG8_MMA(1, 1, At, B1); PG8_BAR;
;     __device__ __forceinline__ void operator()(const Acc& acc, const Unit& u, int wr, int wc, int fr, int fq) const {
;         const int pn = u.pn; const int row0 = u.pm * 256 + wr * 64 + fr;
;         bf16_t* base; int ld, cb; bool act;
;         if (vt) { base = vt; ld = TH; cb = 256 * pn; act = false; }
;         else if (gmode) { base = g; ld = 4096; cb = 256 * pn; act = true; }
;         else if (pn < 8) { base = zna; ld = 2048; cb = 256 * pn; act = false; }
;         else if (pn < 16) { base = zqk; ld = 2048; cb = 256 * (pn - 8); act = false; }
;         else if (pn < 24) { base = vo; ld = 2048; cb = 256 * (pn - 16); act = pn >= 20; }
;         else { base = g; ld = 4096; cb = 256 * (pn - 24); act = true; }
	ds_read_b128 v[158:161], v145 offset:49152
	ds_read_b128 v[162:165], v145 offset:50176
	ds_read_b128 v[166:169], v145 offset:51200
	ds_read_b128 v[170:173], v145 offset:52224
	ds_read_b128 v[174:177], v145 offset:53248
	ds_read_b128 v[178:181], v145 offset:54272
	ds_read_b128 v[204:207], v145 offset:55296
	ds_read_b128 v[208:211], v145 offset:56320
	global_load_lds_dwordx4 v128, s[100:101]
	s_mov_b32 m0, s44
	s_nop 0
	global_load_lds_dwordx4 v130, s[100:101]
	s_barrier
	s_waitcnt lgkmcnt(0)
	s_waitcnt lgkmcnt(0)
	v_mfma_f32_16x16x32_bf16 v[60:63], v[138:141], v[158:161], v[60:63]
	v_mfma_f32_16x16x32_bf16 v[60:63], v[146:149], v[162:165], v[60:63]
	v_mfma_f32_16x16x32_bf16 v[44:47], v[138:141], v[166:169], v[44:47]
	v_mfma_f32_16x16x32_bf16 v[44:47], v[146:149], v[170:173], v[44:47]
	v_mfma_f32_16x16x32_bf16 v[28:31], v[138:141], v[174:177], v[28:31]
	v_mfma_f32_16x16x32_bf16 v[28:31], v[146:149], v[178:181], v[28:31]
	v_mfma_f32_16x16x32_bf16 v[12:15], v[138:141], v[204:207], v[12:15]
	v_mfma_f32_16x16x32_bf16 v[12:15], v[146:149], v[208:211], v[12:15]
	v_mfma_f32_16x16x32_bf16 v[8:11], v[150:153], v[204:207], v[8:11]
	v_mfma_f32_16x16x32_bf16 v[8:11], v[154:157], v[208:211], v[8:11]
	v_mfma_f32_16x16x32_bf16 v[24:27], v[150:153], v[174:177], v[24:27]
	v_mfma_f32_16x16x32_bf16 v[24:27], v[154:157], v[178:181], v[24:27]
	v_mfma_f32_16x16x32_bf16 v[40:43], v[150:153], v[166:169], v[40:43]
	v_mfma_f32_16x16x32_bf16 v[40:43], v[154:157], v[170:173], v[40:43]
	v_mfma_f32_16x16x32_bf16 v[56:59], v[150:153], v[158:161], v[56:59]
	v_mfma_f32_16x16x32_bf16 v[56:59], v[154:157], v[162:165], v[56:59]
	s_barrier
	s_add_u32 s28, s28, 0x80080
	s_addc_u32 s29, s29, 0
	s_add_i32 s30, s30, s38
	s_mov_b32 m0, s30
	s_nop 0
	global_load_lds_dwordx4 v184, s[28:29]
	s_add_i32 m0, s30, 0x2000
	s_nop 0
	global_load_lds_dwordx4 v132, s[28:29]
	s_waitcnt vmcnt(6)
	s_barrier
	v_mfma_f32_16x16x32_bf16 v[52:55], v[212:215], v[158:161], v[52:55]
	v_mfma_f32_16x16x32_bf16 v[52:55], v[216:219], v[162:165], v[52:55]
	v_mfma_f32_16x16x32_bf16 v[36:39], v[212:215], v[166:169], v[36:39]
	v_mfma_f32_16x16x32_bf16 v[36:39], v[216:219], v[170:173], v[36:39]
	v_mfma_f32_16x16x32_bf16 v[20:23], v[212:215], v[174:177], v[20:23]
	v_mfma_f32_16x16x32_bf16 v[20:23], v[216:219], v[178:181], v[20:23]
	v_mfma_f32_16x16x32_bf16 v[4:7], v[212:215], v[204:207], v[4:7]
	v_mfma_f32_16x16x32_bf16 v[4:7], v[216:219], v[208:211], v[4:7]
	v_mfma_f32_16x16x32_bf16 v[0:3], v[220:223], v[204:207], v[0:3]
	v_mfma_f32_16x16x32_bf16 v[0:3], v[224:227], v[208:211], v[0:3]
	v_mfma_f32_16x16x32_bf16 v[16:19], v[220:223], v[174:177], v[16:19]
	v_mfma_f32_16x16x32_bf16 v[16:19], v[224:227], v[178:181], v[16:19]
	v_mfma_f32_16x16x32_bf16 v[32:35], v[220:223], v[166:169], v[32:35]
	v_mfma_f32_16x16x32_bf16 v[32:35], v[224:227], v[170:173], v[32:35]
	v_mfma_f32_16x16x32_bf16 v[48:51], v[220:223], v[158:161], v[48:51]
	v_mfma_f32_16x16x32_bf16 v[48:51], v[224:227], v[162:165], v[48:51]
	s_add_i32 s43, s43, 2
	s_add_u32 s26, s26, 0x100
	s_addc_u32 s27, s27, 0
	s_add_u32 s34, s34, 0x100
	s_addc_u32 s35, s35, 0
	s_cmp_gt_u32 s43, 29
	s_barrier
	s_cbranch_scc0 .LBB0_366
	s_andn2_b64 vcc, exec, s[16:17]
	s_lshl_b32 s1, s8, 8
	s_cbranch_vccnz .LBB0_378
	s_cmp_lt_i32 s8, 8
	s_cbranch_scc1 .LBB0_410
	s_cmp_gt_u32 s8, 15
	s_mov_b64 s[34:35], -1
	s_cbranch_scc0 .LBB0_375
	s_mov_b64 s[30:31], -1
	s_cmp_gt_u32 s8, 23
	s_mov_b64 s[28:29], -1
	s_cbranch_scc0 .LBB0_372
	s_add_i32 s3, s1, 0xffffe800
	s_mov_b64 s[28:29], 0

; #define PG8_STAGE(bufoff, gbase, voff) do { _Pragma("unroll") for (int _i = 0; _i < 2; ++_i) \
;         __builtin_amdgcn_global_load_lds((const unsigned*)((const char*)(gbase) + (voff)[_i]), (LAS unsigned*)(lds + (bufoff) + ldsw + _i * 8192), 16, 0, 0); } while (0)
; #define PG8_LDA(dst, b, h) do { _Pragma("unroll") for (int m = 0; m < 4; ++m) _Pragma("unroll") for (int k = 0; k < 2; ++k) dst[m][k] = *(const LAS bf16x8*)(lds + PG8_SA(b, h) + aoff + m * 2048 + k * 1024); } while (0)
; #define PG8_LDB(dst, b, h) do { _Pragma("unroll") for (int n = 0; n < 2; ++n) _Pragma("unroll") for (int k = 0; k < 2; ++k) dst[n][k] = *(const LAS bf16x8*)(lds + PG8_SB(b, h) + boff + n * 2048 + k * 1024); } while (0)
; #define PG8_MMA(ai, bj, At, Bt) do { __builtin_amdgcn_s_setprio(1); _Pragma("unroll") for (int m = 0; m < 4; ++m) _Pragma("unroll") for (int n = 0; n < 2; ++n) _Pragma("unroll") for (int k = 0; k < 2; ++k) \
;         acc[ai][bj][m][n] = __builtin_amdgcn_mfma_f32_16x16x32_bf16(Bt[n][k], At[m][k], acc[ai][bj][m][n], 0, 0, 0); __builtin_amdgcn_s_setprio(0); } while (0)
; #define PG8_WAIT_L(n) asm volatile("s_waitcnt lgkmcnt(" #n ")" ::: "memory")
; #define PG8_BAR __builtin_amdgcn_s_barrier()
; #define PG8_SCHED __builtin_amdgcn_sched_barrier(0)
; template <class Epi>
; __device__ __forceinline__ void gemm_phase(LAS unsigned char* lds, const Gemm g, const StaticOrder& S, const Epi& E) {
;     ...
;         for (int t = 0; t < nt; t += 2) {
;             const bool last = (t == nt - 2);
;             const char* a1 = cA + (size_t)(t + 1) * kstep;
;             const char* a2 = last ? nA : cA + (size_t)(t + 2) * kstep; const char* b2 = last ? nB : cB + (size_t)(t + 2) * kstep;
;             const char* a3 = a2 + kstep; const char* b3 = b2 + kstep;
;             PG8_LDB(B0, 0, 0); PG8_SCHED; PG8_LDA(At, 0, 0); PG8_STAGE(PG8_SA(1, 1), a1 + hstep, voffA);
;             PG8_WAIT_L(8); PG8_BAR; PG8_WAIT_L(0); PG8_MMA(0, 0, At, B0); PG8_BAR; PG8_SCHED;
;             PG8_LDB(B1, 0, 1); PG8_STAGE(PG8_SB(0, 0), b2, voffB);
;             PG8_BAR; PG8_WAIT_L(0); PG8_MMA(0, 1, At, B1); PG8_BAR;
;             PG8_LDA(At, 0, 1); PG8_STAGE(PG8_SA(0, 0), a2, voffA);
;             PG8_BAR; PG8_WAIT_L(0); PG8_MMA(1, 0, At, B0); PG8_BAR; PG8_SCHED;
;             PG8_STAGE(PG8_SB(0, 1), b2 + hstep, voffB);
.LBB0_490:
	s_add_u32 s30, s8, 0xfff80080
	s_addc_u32 s31, s9, -1
	s_add_i32 s52, 0, 0x10000
	v_add_u32_e32 v154, s52, v143
	ds_read_b128 v[138:141], v154
	ds_read_b128 v[146:149], v154 offset:1024
	ds_read_b128 v[150:153], v154 offset:2048
	ds_read_b128 v[154:157], v154 offset:3072
	s_cmp_eq_u32 s51, 28
	s_cselect_b32 s35, s3, s31
	s_cselect_b32 s34, s21, s30
	s_cselect_b32 s31, s19, s50
	s_cselect_b32 s30, s43, s47
	s_add_i32 m0, s27, 0xc000
	ds_read_b128 v[158:161], v145
	ds_read_b128 v[162:165], v145 offset:1024
	ds_read_b128 v[166:169], v145 offset:2048
	ds_read_b128 v[170:173], v145 offset:3072
	ds_read_b128 v[174:177], v145 offset:4096
	ds_read_b128 v[178:181], v145 offset:5120
	ds_read_b128 v[204:207], v145 offset:6144
	ds_read_b128 v[208:211], v145 offset:7168
	global_load_lds_dwordx4 v134, s[8:9]
	s_add_i32 m0, s27, 0xe000
	s_nop 0
	global_load_lds_dwordx4 v136, s[8:9]
	s_waitcnt lgkmcnt(8)
	s_barrier
	s_waitcnt lgkmcnt(0)
	s_waitcnt lgkmcnt(0)
	v_mfma_f32_16x16x32_bf16 v[124:127], v[138:141], v[158:161], v[124:127]
	v_mfma_f32_16x16x32_bf16 v[124:127], v[146:149], v[162:165], v[124:127]
	v_mfma_f32_16x16x32_bf16 v[108:111], v[138:141], v[166:169], v[108:111]
	v_mfma_f32_16x16x32_bf16 v[108:111], v[146:149], v[170:173], v[108:111]
	v_mfma_f32_16x16x32_bf16 v[92:95], v[138:141], v[174:177], v[92:95]
	v_mfma_f32_16x16x32_bf16 v[92:95], v[146:149], v[178:181], v[92:95]
	v_mfma_f32_16x16x32_bf16 v[76:79], v[138:141], v[204:207], v[76:79]
	v_mfma_f32_16x16x32_bf16 v[76:79], v[146:149], v[208:211], v[76:79]
	v_mfma_f32_16x16x32_bf16 v[72:75], v[150:153], v[204:207], v[72:75]
	v_mfma_f32_16x16x32_bf16 v[72:75], v[154:157], v[208:211], v[72:75]
	v_mfma_f32_16x16x32_bf16 v[88:91], v[150:153], v[174:177], v[88:91]
	v_mfma_f32_16x16x32_bf16 v[88:91], v[154:157], v[178:181], v[88:91]
	v_mfma_f32_16x16x32_bf16 v[104:107], v[150:153], v[166:169], v[104:107]
	v_mfma_f32_16x16x32_bf16 v[104:107], v[154:157], v[170:173], v[104:107]
	v_mfma_f32_16x16x32_bf16 v[120:123], v[150:153], v[158:161], v[120:123]
	v_mfma_f32_16x16x32_bf16 v[120:123], v[154:157], v[162:165], v[120:123]
	s_barrier
	s_add_i32 s56, 0, 0x14000
	v_add_u32_e32 v182, s56, v143
	s_add_i32 s52, s52, s38
	ds_read_b128 v[212:215], v182
	ds_read_b128 v[216:219], v182 offset:1024
	ds_read_b128 v[220:223], v182 offset:2048
	ds_read_b128 v[224:227], v182 offset:3072
	s_mov_b32 m0, s52
	s_add_u32 s98, s30, s58
	s_addc_u32 s99, s31, s59
	global_load_lds_dwordx4 v184, s[30:31]
	s_add_i32 m0, s52, 0x2000
	s_nop 0
	global_load_lds_dwordx4 v132, s[30:31]
	s_barrier
	s_waitcnt lgkmcnt(0)
	s_waitcnt lgkmcnt(0)
	v_mfma_f32_16x16x32_bf16 v[116:119], v[212:215], v[158:161], v[116:119]
	v_mfma_f32_16x16x32_bf16 v[116:119], v[216:219], v[162:165], v[116:119]
	v_mfma_f32_16x16x32_bf16 v[100:103], v[212:215], v[166:169], v[100:103]
	v_mfma_f32_16x16x32_bf16 v[100:103], v[216:219], v[170:173], v[100:103]
	v_mfma_f32_16x16x32_bf16 v[84:87], v[212:215], v[174:177], v[84:87]
	v_mfma_f32_16x16x32_bf16 v[84:87], v[216:219], v[178:181], v[84:87]
	v_mfma_f32_16x16x32_bf16 v[68:71], v[212:215], v[204:207], v[68:71]
	v_mfma_f32_16x16x32_bf16 v[68:71], v[216:219], v[208:211], v[68:71]
	v_mfma_f32_16x16x32_bf16 v[64:67], v[220:223], v[204:207], v[64:67]
	v_mfma_f32_16x16x32_bf16 v[64:67], v[224:227], v[208:211], v[64:67]
	v_mfma_f32_16x16x32_bf16 v[80:83], v[220:223], v[174:177], v[80:83]
	v_mfma_f32_16x16x32_bf16 v[80:83], v[224:227], v[178:181], v[80:83]
	v_mfma_f32_16x16x32_bf16 v[96:99], v[220:223], v[166:169], v[96:99]
	v_mfma_f32_16x16x32_bf16 v[96:99], v[224:227], v[170:173], v[96:99]
	v_mfma_f32_16x16x32_bf16 v[112:115], v[220:223], v[158:161], v[112:115]
	v_mfma_f32_16x16x32_bf16 v[112:115], v[224:227], v[162:165], v[112:115]
	s_mov_b32 m0, s27
	s_barrier
	ds_read_b128 v[158:161], v145 offset:16384
	ds_read_b128 v[162:165], v145 offset:17408
	ds_read_b128 v[166:169], v145 offset:18432
	ds_read_b128 v[170:173], v145 offset:19456
	ds_read_b128 v[174:177], v145 offset:20480
	ds_read_b128 v[178:181], v145 offset:21504
	ds_read_b128 v[204:207], v145 offset:22528
	ds_read_b128 v[208:211], v145 offset:23552
	global_load_lds_dwordx4 v128, s[34:35]
	s_add_u32 s100, s34, s58
	s_addc_u32 s101, s35, s59
	s_mov_b32 m0, s29
	s_nop 0
	global_load_lds_dwordx4 v130, s[34:35]
	s_barrier
	s_waitcnt lgkmcnt(0)
	s_waitcnt lgkmcnt(0)
	v_mfma_f32_16x16x32_bf16 v[60:63], v[138:141], v[158:161], v[60:63]
	v_mfma_f32_16x16x32_bf16 v[60:63], v[146:149], v[162:165], v[60:63]
	v_mfma_f32_16x16x32_bf16 v[44:47], v[138:141], v[166:169], v[44:47]
	v_mfma_f32_16x16x32_bf16 v[44:47], v[146:149], v[170:173], v[44:47]
	v_mfma_f32_16x16x32_bf16 v[28:31], v[138:141], v[174:177], v[28:31]
	v_mfma_f32_16x16x32_bf16 v[28:31], v[146:149], v[178:181], v[28:31]
	v_mfma_f32_16x16x32_bf16 v[12:15], v[138:141], v[204:207], v[12:15]
	v_mfma_f32_16x16x32_bf16 v[12:15], v[146:149], v[208:211], v[12:15]
	v_mfma_f32_16x16x32_bf16 v[8:11], v[150:153], v[204:207], v[8:11]
	v_mfma_f32_16x16x32_bf16 v[8:11], v[154:157], v[208:211], v[8:11]
	v_mfma_f32_16x16x32_bf16 v[24:27], v[150:153], v[174:177], v[24:27]
	v_mfma_f32_16x16x32_bf16 v[24:27], v[154:157], v[178:181], v[24:27]
	v_mfma_f32_16x16x32_bf16 v[40:43], v[150:153], v[166:169], v[40:43]
	v_mfma_f32_16x16x32_bf16 v[40:43], v[154:157], v[170:173], v[40:43]
	v_mfma_f32_16x16x32_bf16 v[56:59], v[150:153], v[158:161], v[56:59]
	v_mfma_f32_16x16x32_bf16 v[56:59], v[154:157], v[162:165], v[56:59]
	s_barrier
	s_add_u32 s54, s30, 0x80000
	s_addc_u32 s55, s31, 0
	s_add_i32 s52, s56, s38
	s_mov_b32 m0, s52
	s_nop 0
	global_load_lds_dwordx4 v184, s[54:55]
	s_add_i32 m0, s52, 0x2000
	s_nop 0
	global_load_lds_dwordx4 v132, s[54:55]
	s_waitcnt vmcnt(6)
	s_barrier
; #define PG8_STAGE(bufoff, gbase, voff) do { _Pragma("unroll") for (int _i = 0; _i < 2; ++_i) \
;         __builtin_amdgcn_global_load_lds((const unsigned*)((const char*)(gbase) + (voff)[_i]), (LAS unsigned*)(lds + (bufoff) + ldsw + _i * 8192), 16, 0, 0); } while (0)
; #define PG8_LDA(dst, b, h) do { _Pragma("unroll") for (int m = 0; m < 4; ++m) _Pragma("unroll") for (int k = 0; k < 2; ++k) dst[m][k] = *(const LAS bf16x8*)(lds + PG8_SA(b, h) + aoff + m * 2048 + k * 1024); } while (0)
; #define PG8_LDB(dst, b, h) do { _Pragma("unroll") for (int n = 0; n < 2; ++n) _Pragma("unroll") for (int k = 0; k < 2; ++k) dst[n][k] = *(const LAS bf16x8*)(lds + PG8_SB(b, h) + boff + n * 2048 + k * 1024); } while (0)
; #define PG8_MMA(ai, bj, At, Bt) do { __builtin_amdgcn_s_setprio(1); _Pragma("unroll") for (int m = 0; m < 4; ++m) _Pragma("unroll") for (int n = 0; n < 2; ++n) _Pragma("unroll") for (int k = 0; k < 2; ++k) \
;         acc[ai][bj][m][n] = __builtin_amdgcn_mfma_f32_16x16x32_bf16(Bt[n][k], At[m][k], acc[ai][bj][m][n], 0, 0, 0); __builtin_amdgcn_s_setprio(0); } while (0)
; #define PG8_WAIT_V(n) asm volatile("s_waitcnt vmcnt(" #n ")" ::: "memory")
; #define PG8_WAIT_L(n) asm volatile("s_waitcnt lgkmcnt(" #n ")" ::: "memory")
; #define PG8_BAR __builtin_amdgcn_s_barrier()
; #define PG8_SCHED __builtin_amdgcn_sched_barrier(0)
; template <class Epi>
; __device__ __forceinline__ void gemm_phase(LAS unsigned char* lds, const Gemm g, const StaticOrder& S, const Epi& E) {
;     ...
;             PG8_WAIT_V(6); PG8_BAR; PG8_MMA(1, 1, At, B1); PG8_BAR;
;             PG8_LDB(B0, 1, 0); PG8_SCHED; PG8_LDA(At, 1, 0); PG8_STAGE(PG8_SA(0, 1), a2 + hstep, voffA);
;             PG8_WAIT_L(8); PG8_BAR; PG8_WAIT_L(0); PG8_MMA(0, 0, At, B0); PG8_BAR; PG8_SCHED;
;             PG8_LDB(B1, 1, 1); PG8_STAGE(PG8_SB(1, 0), b3, voffB);
;             PG8_BAR; PG8_WAIT_L(0); PG8_MMA(0, 1, At, B1); PG8_BAR;
	v_mfma_f32_16x16x32_bf16 v[52:55], v[212:215], v[158:161], v[52:55]
	v_mfma_f32_16x16x32_bf16 v[52:55], v[216:219], v[162:165], v[52:55]
	v_mfma_f32_16x16x32_bf16 v[36:39], v[212:215], v[166:169], v[36:39]
	v_mfma_f32_16x16x32_bf16 v[36:39], v[216:219], v[170:173], v[36:39]
	v_mfma_f32_16x16x32_bf16 v[20:23], v[212:215], v[174:177], v[20:23]
	v_mfma_f32_16x16x32_bf16 v[20:23], v[216:219], v[178:181], v[20:23]
	v_mfma_f32_16x16x32_bf16 v[4:7], v[212:215], v[204:207], v[4:7]
	v_mfma_f32_16x16x32_bf16 v[4:7], v[216:219], v[208:211], v[4:7]
	v_mfma_f32_16x16x32_bf16 v[0:3], v[220:223], v[204:207], v[0:3]
	v_mfma_f32_16x16x32_bf16 v[0:3], v[224:227], v[208:211], v[0:3]
	v_mfma_f32_16x16x32_bf16 v[16:19], v[220:223], v[174:177], v[16:19]
	v_mfma_f32_16x16x32_bf16 v[16:19], v[224:227], v[178:181], v[16:19]
	v_mfma_f32_16x16x32_bf16 v[32:35], v[220:223], v[166:169], v[32:35]
	v_mfma_f32_16x16x32_bf16 v[32:35], v[224:227], v[170:173], v[32:35]
	v_mfma_f32_16x16x32_bf16 v[48:51], v[220:223], v[158:161], v[48:51]
	v_mfma_f32_16x16x32_bf16 v[48:51], v[224:227], v[162:165], v[48:51]
	s_add_i32 s52, 0, 0x18000
	v_add_u32_e32 v154, s52, v143
	s_barrier
	ds_read_b128 v[138:141], v154
	ds_read_b128 v[146:149], v154 offset:1024
	ds_read_b128 v[150:153], v154 offset:2048
	ds_read_b128 v[154:157], v154 offset:3072
	s_add_u32 s34, s34, 0x80000
	s_addc_u32 s35, s35, 0
	s_mov_b32 m0, s39
	ds_read_b128 v[158:161], v145 offset:32768
	ds_read_b128 v[162:165], v145 offset:33792
	ds_read_b128 v[166:169], v145 offset:34816
	ds_read_b128 v[170:173], v145 offset:35840
	ds_read_b128 v[174:177], v145 offset:36864
	ds_read_b128 v[178:181], v145 offset:37888
	ds_read_b128 v[204:207], v145 offset:38912
	ds_read_b128 v[208:211], v145 offset:39936
	global_load_lds_dwordx4 v128, s[34:35]
	s_mov_b32 m0, s40
	s_nop 0
	global_load_lds_dwordx4 v130, s[34:35]
	s_waitcnt lgkmcnt(8)
	s_barrier
	s_waitcnt lgkmcnt(0)
	s_waitcnt lgkmcnt(0)
	v_mfma_f32_16x16x32_bf16 v[124:127], v[138:141], v[158:161], v[124:127]
	v_mfma_f32_16x16x32_bf16 v[124:127], v[146:149], v[162:165], v[124:127]
	v_mfma_f32_16x16x32_bf16 v[108:111], v[138:141], v[166:169], v[108:111]
	v_mfma_f32_16x16x32_bf16 v[108:111], v[146:149], v[170:173], v[108:111]
	v_mfma_f32_16x16x32_bf16 v[92:95], v[138:141], v[174:177], v[92:95]
	v_mfma_f32_16x16x32_bf16 v[92:95], v[146:149], v[178:181], v[92:95]
	v_mfma_f32_16x16x32_bf16 v[76:79], v[138:141], v[204:207], v[76:79]
	v_mfma_f32_16x16x32_bf16 v[76:79], v[146:149], v[208:211], v[76:79]
	v_mfma_f32_16x16x32_bf16 v[72:75], v[150:153], v[204:207], v[72:75]
	v_mfma_f32_16x16x32_bf16 v[72:75], v[154:157], v[208:211], v[72:75]
	v_mfma_f32_16x16x32_bf16 v[88:91], v[150:153], v[174:177], v[88:91]
	v_mfma_f32_16x16x32_bf16 v[88:91], v[154:157], v[178:181], v[88:91]
	v_mfma_f32_16x16x32_bf16 v[104:107], v[150:153], v[166:169], v[104:107]
	v_mfma_f32_16x16x32_bf16 v[104:107], v[154:157], v[170:173], v[104:107]
	v_mfma_f32_16x16x32_bf16 v[120:123], v[150:153], v[158:161], v[120:123]
	v_mfma_f32_16x16x32_bf16 v[120:123], v[154:157], v[162:165], v[120:123]
	s_barrier
	s_add_i32 s34, 0, 0x1c000
	s_add_i32 s35, s52, s38
	v_add_u32_e32 v187, s34, v143
	s_mov_b32 m0, s35
	ds_read_b128 v[212:215], v187
	ds_read_b128 v[216:219], v187 offset:1024
	ds_read_b128 v[220:223], v187 offset:2048
	ds_read_b128 v[224:227], v187 offset:3072
	global_load_lds_dwordx4 v184, s[98:99]
	s_add_i32 m0, s35, 0x2000
	s_nop 0
	global_load_lds_dwordx4 v132, s[98:99]
	s_barrier
	s_waitcnt lgkmcnt(0)
	s_waitcnt lgkmcnt(0)
	v_mfma_f32_16x16x32_bf16 v[116:119], v[212:215], v[158:161], v[116:119]
	v_mfma_f32_16x16x32_bf16 v[116:119], v[216:219], v[162:165], v[116:119]
	v_mfma_f32_16x16x32_bf16 v[100:103], v[212:215], v[166:169], v[100:103]
	v_mfma_f32_16x16x32_bf16 v[100:103], v[216:219], v[170:173], v[100:103]
	v_mfma_f32_16x16x32_bf16 v[84:87], v[212:215], v[174:177], v[84:87]
	v_mfma_f32_16x16x32_bf16 v[84:87], v[216:219], v[178:181], v[84:87]
	v_mfma_f32_16x16x32_bf16 v[68:71], v[212:215], v[204:207], v[68:71]
	v_mfma_f32_16x16x32_bf16 v[68:71], v[216:219], v[208:211], v[68:71]
	v_mfma_f32_16x16x32_bf16 v[64:67], v[220:223], v[204:207], v[64:67]
	v_mfma_f32_16x16x32_bf16 v[64:67], v[224:227], v[208:211], v[64:67]
	v_mfma_f32_16x16x32_bf16 v[80:83], v[220:223], v[174:177], v[80:83]
	v_mfma_f32_16x16x32_bf16 v[80:83], v[224:227], v[178:181], v[80:83]
	v_mfma_f32_16x16x32_bf16 v[96:99], v[220:223], v[166:169], v[96:99]
	v_mfma_f32_16x16x32_bf16 v[96:99], v[224:227], v[170:173], v[96:99]
	v_mfma_f32_16x16x32_bf16 v[112:115], v[220:223], v[158:161], v[112:115]
	v_mfma_f32_16x16x32_bf16 v[112:115], v[224:227], v[162:165], v[112:115]
	s_mov_b32 m0, s41
	s_barrier
; __device__ __forceinline__ float sigmoidf_(float x) { return __builtin_amdgcn_rcpf(1.0f + __builtin_amdgcn_exp2f(-1.4426950408889634f * x)); }
; #define PG8_STAGE(bufoff, gbase, voff) do { _Pragma("unroll") for (int _i = 0; _i < 2; ++_i) \
;         __builtin_amdgcn_global_load_lds((const unsigned*)((const char*)(gbase) + (voff)[_i]), (LAS unsigned*)(lds + (bufoff) + ldsw + _i * 8192), 16, 0, 0); } while (0)
; #define PG8_LDA(dst, b, h) do { _Pragma("unroll") for (int m = 0; m < 4; ++m) _Pragma("unroll") for (int k = 0; k < 2; ++k) dst[m][k] = *(const LAS bf16x8*)(lds + PG8_SA(b, h) + aoff + m * 2048 + k * 1024); } while (0)
; #define PG8_MMA(ai, bj, At, Bt) do { __builtin_amdgcn_s_setprio(1); _Pragma("unroll") for (int m = 0; m < 4; ++m) _Pragma("unroll") for (int n = 0; n < 2; ++n) _Pragma("unroll") for (int k = 0; k < 2; ++k) \
;         acc[ai][bj][m][n] = __builtin_amdgcn_mfma_f32_16x16x32_bf16(Bt[n][k], At[m][k], acc[ai][bj][m][n], 0, 0, 0); __builtin_amdgcn_s_setprio(0); } while (0)
; #define PG8_WAIT_V(n) asm volatile("s_waitcnt vmcnt(" #n ")" ::: "memory")
; #define PG8_WAIT_L(n) asm volatile("s_waitcnt lgkmcnt(" #n ")" ::: "memory")
; #define PG8_BAR __builtin_amdgcn_s_barrier()
; #define PG8_SCHED __builtin_amdgcn_sched_barrier(0)
; template <class Epi>
; __device__ __forceinline__ void gemm_phase(LAS unsigned char* lds, const Gemm g, const StaticOrder& S, const Epi& E) {
;     ...
;             PG8_LDA(At, 1, 1); PG8_STAGE(PG8_SA(1, 0), a3, voffA);
;             PG8_BAR; PG8_WAIT_L(0); PG8_MMA(1, 0, At, B0); PG8_BAR; PG8_SCHED;
;             PG8_STAGE(PG8_SB(1, 1), b3 + hstep, voffB);
;             PG8_WAIT_V(6); PG8_BAR; PG8_MMA(1, 1, At, B1); PG8_BAR;
;     __device__ __forceinline__ void operator()(const Acc& acc, const Unit& u, int wr, int wc, int fr, int fq) const {
;     ...
;                 for (int bj = 0; bj < 2; ++bj) { f32x4 v0 = acc[ai][bj][m][0], v1 = acc[ai][bj][m][1];
;                     if (act) {
; #pragma unroll
;                         for (int j = 0; j < 4; ++j) { v0[j] = sigmoidf_(v0[j]); v1[j] = sigmoidf_(v1[j]); } }
	ds_read_b128 v[158:161], v145 offset:49152
	ds_read_b128 v[162:165], v145 offset:50176
	ds_read_b128 v[166:169], v145 offset:51200
	ds_read_b128 v[170:173], v145 offset:52224
	ds_read_b128 v[174:177], v145 offset:53248
	ds_read_b128 v[178:181], v145 offset:54272
	ds_read_b128 v[204:207], v145 offset:55296
	ds_read_b128 v[208:211], v145 offset:56320
	global_load_lds_dwordx4 v128, s[100:101]
	s_mov_b32 m0, s42
	s_nop 0
	global_load_lds_dwordx4 v130, s[100:101]
	s_barrier
	s_waitcnt lgkmcnt(0)
	s_waitcnt lgkmcnt(0)
	v_mfma_f32_16x16x32_bf16 v[60:63], v[138:141], v[158:161], v[60:63]
	v_mfma_f32_16x16x32_bf16 v[60:63], v[146:149], v[162:165], v[60:63]
	v_mfma_f32_16x16x32_bf16 v[44:47], v[138:141], v[166:169], v[44:47]
	v_mfma_f32_16x16x32_bf16 v[44:47], v[146:149], v[170:173], v[44:47]
	v_mfma_f32_16x16x32_bf16 v[28:31], v[138:141], v[174:177], v[28:31]
	v_mfma_f32_16x16x32_bf16 v[28:31], v[146:149], v[178:181], v[28:31]
	v_mfma_f32_16x16x32_bf16 v[12:15], v[138:141], v[204:207], v[12:15]
	v_mfma_f32_16x16x32_bf16 v[12:15], v[146:149], v[208:211], v[12:15]
	v_mfma_f32_16x16x32_bf16 v[8:11], v[150:153], v[204:207], v[8:11]
	v_mfma_f32_16x16x32_bf16 v[8:11], v[154:157], v[208:211], v[8:11]
	v_mfma_f32_16x16x32_bf16 v[24:27], v[150:153], v[174:177], v[24:27]
	v_mfma_f32_16x16x32_bf16 v[24:27], v[154:157], v[178:181], v[24:27]
	v_mfma_f32_16x16x32_bf16 v[40:43], v[150:153], v[166:169], v[40:43]
	v_mfma_f32_16x16x32_bf16 v[40:43], v[154:157], v[170:173], v[40:43]
	v_mfma_f32_16x16x32_bf16 v[56:59], v[150:153], v[158:161], v[56:59]
	v_mfma_f32_16x16x32_bf16 v[56:59], v[154:157], v[162:165], v[56:59]
	s_barrier
	s_add_u32 s30, s30, 0x80080
	s_addc_u32 s31, s31, 0
	s_add_i32 s34, s34, s38
	s_mov_b32 m0, s34
	s_nop 0
	global_load_lds_dwordx4 v184, s[30:31]
	s_add_i32 m0, s34, 0x2000
	s_nop 0
	global_load_lds_dwordx4 v132, s[30:31]
	s_waitcnt vmcnt(6)
	s_barrier
	v_mfma_f32_16x16x32_bf16 v[52:55], v[212:215], v[158:161], v[52:55]
	v_mfma_f32_16x16x32_bf16 v[52:55], v[216:219], v[162:165], v[52:55]
	v_mfma_f32_16x16x32_bf16 v[36:39], v[212:215], v[166:169], v[36:39]
	v_mfma_f32_16x16x32_bf16 v[36:39], v[216:219], v[170:173], v[36:39]
	v_mfma_f32_16x16x32_bf16 v[20:23], v[212:215], v[174:177], v[20:23]
	v_mfma_f32_16x16x32_bf16 v[20:23], v[216:219], v[178:181], v[20:23]
	v_mfma_f32_16x16x32_bf16 v[4:7], v[212:215], v[204:207], v[4:7]
	v_mfma_f32_16x16x32_bf16 v[4:7], v[216:219], v[208:211], v[4:7]
	v_mfma_f32_16x16x32_bf16 v[0:3], v[220:223], v[204:207], v[0:3]
	v_mfma_f32_16x16x32_bf16 v[0:3], v[224:227], v[208:211], v[0:3]
	v_mfma_f32_16x16x32_bf16 v[16:19], v[220:223], v[174:177], v[16:19]
	v_mfma_f32_16x16x32_bf16 v[16:19], v[224:227], v[178:181], v[16:19]
	v_mfma_f32_16x16x32_bf16 v[32:35], v[220:223], v[166:169], v[32:35]
	v_mfma_f32_16x16x32_bf16 v[32:35], v[224:227], v[170:173], v[32:35]
	v_mfma_f32_16x16x32_bf16 v[48:51], v[220:223], v[158:161], v[48:51]
	v_mfma_f32_16x16x32_bf16 v[48:51], v[224:227], v[162:165], v[48:51]
	s_add_i32 s51, s51, 2
	s_add_u32 s8, s8, 0x100
	s_addc_u32 s9, s9, 0
	s_add_u32 s47, s47, 0x100
	s_addc_u32 s50, s50, 0
	s_cmp_gt_u32 s51, 29
	s_barrier
	s_cbranch_scc0 .LBB0_490
	v_cndmask_b32_e64 v138, 0, 1, s[16:17]
	v_cmp_ne_u32_e64 s[8:9], 1, v138
	s_andn2_b64 vcc, exec, s[16:17]
	s_cbranch_vccnz .LBB0_493
	v_mul_f32_e32 v124, 0xbfb8aa3b, v124
	v_mul_f32_e32 v120, 0xbfb8aa3b, v120
	v_mul_f32_e32 v125, 0xbfb8aa3b, v125
	v_mul_f32_e32 v121, 0xbfb8aa3b, v121
	v_mul_f32_e32 v126, 0xbfb8aa3b, v126
	v_mul_f32_e32 v122, 0xbfb8aa3b, v122
	v_mul_f32_e32 v127, 0xbfb8aa3b, v127
	v_mul_f32_e32 v123, 0xbfb8aa3b, v123
	v_exp_f32_e32 v124, v124
	v_exp_f32_e32 v120, v120
	v_exp_f32_e32 v125, v125
	v_exp_f32_e32 v121, v121
	v_exp_f32_e32 v126, v126
	v_exp_f32_e32 v122, v122
	v_exp_f32_e32 v127, v127
	v_exp_f32_e32 v123, v123
	v_add_f32_e32 v124, 1.0, v124
	v_add_f32_e32 v120, 1.0, v120
	v_add_f32_e32 v125, 1.0, v125
	v_add_f32_e32 v121, 1.0, v121
	v_add_f32_e32 v126, 1.0, v126
	v_add_f32_e32 v122, 1.0, v122
	v_add_f32_e32 v127, 1.0, v127
	v_add_f32_e32 v123, 1.0, v123
	v_rcp_f32_e32 v124, v124
	v_rcp_f32_e32 v120, v120
	v_rcp_f32_e32 v125, v125
	v_rcp_f32_e32 v121, v121
	v_rcp_f32_e32 v126, v126
	v_rcp_f32_e32 v122, v122
	v_rcp_f32_e32 v127, v127
	v_rcp_f32_e32 v123, v123

; #define PG8_STAGE(bufoff, gbase, voff) do { _Pragma("unroll") for (int _i = 0; _i < 2; ++_i) \
;         __builtin_amdgcn_global_load_lds((const unsigned*)((const char*)(gbase) + (voff)[_i]), (LAS unsigned*)(lds + (bufoff) + ldsw + _i * 8192), 16, 0, 0); } while (0)
; #define PG8_LDA(dst, b, h) do { _Pragma("unroll") for (int m = 0; m < 4; ++m) _Pragma("unroll") for (int k = 0; k < 2; ++k) dst[m][k] = *(const LAS bf16x8*)(lds + PG8_SA(b, h) + aoff + m * 2048 + k * 1024); } while (0)
; #define PG8_LDB(dst, b, h) do { _Pragma("unroll") for (int n = 0; n < 2; ++n) _Pragma("unroll") for (int k = 0; k < 2; ++k) dst[n][k] = *(const LAS bf16x8*)(lds + PG8_SB(b, h) + boff + n * 2048 + k * 1024); } while (0)
; #define PG8_MMA(ai, bj, At, Bt) do { __builtin_amdgcn_s_setprio(1); _Pragma("unroll") for (int m = 0; m < 4; ++m) _Pragma("unroll") for (int n = 0; n < 2; ++n) _Pragma("unroll") for (int k = 0; k < 2; ++k) \
;         acc[ai][bj][m][n] = __builtin_amdgcn_mfma_f32_16x16x32_bf16(Bt[n][k], At[m][k], acc[ai][bj][m][n], 0, 0, 0); __builtin_amdgcn_s_setprio(0); } while (0)
; #define PG8_WAIT_L(n) asm volatile("s_waitcnt lgkmcnt(" #n ")" ::: "memory")
; #define PG8_BAR __builtin_amdgcn_s_barrier()
; #define PG8_SCHED __builtin_amdgcn_sched_barrier(0)
; template <class Epi>
; __device__ __forceinline__ void gemm_phase(LAS unsigned char* lds, const Gemm g, const StaticOrder& S, const Epi& E) {
;     ...
;         for (int t = 0; t < nt; t += 2) {
;             const bool last = (t == nt - 2);
;             const char* a1 = cA + (size_t)(t + 1) * kstep;
;             const char* a2 = last ? nA : cA + (size_t)(t + 2) * kstep; const char* b2 = last ? nB : cB + (size_t)(t + 2) * kstep;
;             const char* a3 = a2 + kstep; const char* b3 = b2 + kstep;
;             PG8_LDB(B0, 0, 0); PG8_SCHED; PG8_LDA(At, 0, 0); PG8_STAGE(PG8_SA(1, 1), a1 + hstep, voffA);
;             PG8_WAIT_L(8); PG8_BAR; PG8_WAIT_L(0); PG8_MMA(0, 0, At, B0); PG8_BAR; PG8_SCHED;
;             PG8_LDB(B1, 0, 1); PG8_STAGE(PG8_SB(0, 0), b2, voffB);
;             PG8_BAR; PG8_WAIT_L(0); PG8_MMA(0, 1, At, B1); PG8_BAR;
;             PG8_LDA(At, 0, 1); PG8_STAGE(PG8_SA(0, 0), a2, voffA);
;             PG8_BAR; PG8_WAIT_L(0); PG8_MMA(1, 0, At, B0); PG8_BAR; PG8_SCHED;
;             PG8_STAGE(PG8_SB(0, 1), b2 + hstep, voffB);
.LBB0_721:
	s_add_u32 s18, s16, 0xfff80080
	s_addc_u32 s19, s17, -1
	s_add_i32 s39, 0, 0x10000
	v_add_u32_e32 v154, s39, v139
	ds_read_b128 v[142:145], v154
	ds_read_b128 v[146:149], v154 offset:1024
	ds_read_b128 v[150:153], v154 offset:2048
	ds_read_b128 v[154:157], v154 offset:3072
	s_cmp_eq_u32 s38, 28
	s_cselect_b32 s21, s9, s19
	s_cselect_b32 s20, s34, s18
	s_cselect_b32 s19, s1, s37
	s_cselect_b32 s18, s35, s36
	s_add_i32 m0, s15, 0xc000
	ds_read_b128 v[158:161], v141
	ds_read_b128 v[162:165], v141 offset:1024
	ds_read_b128 v[166:169], v141 offset:2048
	ds_read_b128 v[170:173], v141 offset:3072
	ds_read_b128 v[174:177], v141 offset:4096
	ds_read_b128 v[178:181], v141 offset:5120
	ds_read_b128 v[208:211], v141 offset:6144
	ds_read_b128 v[212:215], v141 offset:7168
	global_load_lds_dwordx4 v134, s[16:17]
	s_add_i32 m0, s15, 0xe000
	s_nop 0
	global_load_lds_dwordx4 v136, s[16:17]
	s_waitcnt lgkmcnt(8)
	s_barrier
	s_waitcnt lgkmcnt(0)
	s_waitcnt lgkmcnt(0)
	v_mfma_f32_16x16x32_bf16 v[124:127], v[142:145], v[158:161], v[124:127]
	v_mfma_f32_16x16x32_bf16 v[124:127], v[146:149], v[162:165], v[124:127]
	v_mfma_f32_16x16x32_bf16 v[108:111], v[142:145], v[166:169], v[108:111]
	v_mfma_f32_16x16x32_bf16 v[108:111], v[146:149], v[170:173], v[108:111]
	v_mfma_f32_16x16x32_bf16 v[92:95], v[142:145], v[174:177], v[92:95]
	v_mfma_f32_16x16x32_bf16 v[92:95], v[146:149], v[178:181], v[92:95]
	v_mfma_f32_16x16x32_bf16 v[76:79], v[142:145], v[208:211], v[76:79]
	v_mfma_f32_16x16x32_bf16 v[76:79], v[146:149], v[212:215], v[76:79]
	v_mfma_f32_16x16x32_bf16 v[68:71], v[150:153], v[208:211], v[68:71]
	v_mfma_f32_16x16x32_bf16 v[68:71], v[154:157], v[212:215], v[68:71]
	v_mfma_f32_16x16x32_bf16 v[84:87], v[150:153], v[174:177], v[84:87]
	v_mfma_f32_16x16x32_bf16 v[84:87], v[154:157], v[178:181], v[84:87]
	v_mfma_f32_16x16x32_bf16 v[100:103], v[150:153], v[166:169], v[100:103]
	v_mfma_f32_16x16x32_bf16 v[100:103], v[154:157], v[170:173], v[100:103]
	v_mfma_f32_16x16x32_bf16 v[116:119], v[150:153], v[158:161], v[116:119]
	v_mfma_f32_16x16x32_bf16 v[116:119], v[154:157], v[162:165], v[116:119]
	s_barrier
	s_add_i32 s42, 0, 0x14000
	v_add_u32_e32 v182, s42, v139
	s_add_i32 s39, s39, s24
	ds_read_b128 v[216:219], v182
	ds_read_b128 v[220:223], v182 offset:1024
	ds_read_b128 v[224:227], v182 offset:2048
	ds_read_b128 v[228:231], v182 offset:3072
	s_mov_b32 m0, s39
	s_add_u32 s98, s18, s58
	s_addc_u32 s99, s19, s59
	global_load_lds_dwordx4 v184, s[18:19]
	s_add_i32 m0, s39, 0x2000
	s_nop 0
	global_load_lds_dwordx4 v128, s[18:19]
	s_barrier
	s_waitcnt lgkmcnt(0)
	s_waitcnt lgkmcnt(0)
	v_mfma_f32_16x16x32_bf16 v[120:123], v[216:219], v[158:161], v[120:123]
	v_mfma_f32_16x16x32_bf16 v[120:123], v[220:223], v[162:165], v[120:123]
	v_mfma_f32_16x16x32_bf16 v[104:107], v[216:219], v[166:169], v[104:107]
	v_mfma_f32_16x16x32_bf16 v[104:107], v[220:223], v[170:173], v[104:107]
	v_mfma_f32_16x16x32_bf16 v[88:91], v[216:219], v[174:177], v[88:91]
	v_mfma_f32_16x16x32_bf16 v[88:91], v[220:223], v[178:181], v[88:91]
	v_mfma_f32_16x16x32_bf16 v[72:75], v[216:219], v[208:211], v[72:75]
	v_mfma_f32_16x16x32_bf16 v[72:75], v[220:223], v[212:215], v[72:75]
	v_mfma_f32_16x16x32_bf16 v[64:67], v[224:227], v[208:211], v[64:67]
	v_mfma_f32_16x16x32_bf16 v[64:67], v[228:231], v[212:215], v[64:67]
	v_mfma_f32_16x16x32_bf16 v[80:83], v[224:227], v[174:177], v[80:83]
	v_mfma_f32_16x16x32_bf16 v[80:83], v[228:231], v[178:181], v[80:83]
	v_mfma_f32_16x16x32_bf16 v[96:99], v[224:227], v[166:169], v[96:99]
	v_mfma_f32_16x16x32_bf16 v[96:99], v[228:231], v[170:173], v[96:99]
	v_mfma_f32_16x16x32_bf16 v[112:115], v[224:227], v[158:161], v[112:115]
	v_mfma_f32_16x16x32_bf16 v[112:115], v[228:231], v[162:165], v[112:115]
	s_mov_b32 m0, s15
	s_barrier
	ds_read_b128 v[158:161], v141 offset:16384
	ds_read_b128 v[162:165], v141 offset:17408
	ds_read_b128 v[166:169], v141 offset:18432
	ds_read_b128 v[170:173], v141 offset:19456
	ds_read_b128 v[174:177], v141 offset:20480
	ds_read_b128 v[178:181], v141 offset:21504
	ds_read_b128 v[208:211], v141 offset:22528
	ds_read_b128 v[212:215], v141 offset:23552
	global_load_lds_dwordx4 v132, s[20:21]
	s_add_u32 s100, s20, s58
	s_addc_u32 s101, s21, s59
	s_mov_b32 m0, s26
	s_nop 0
	global_load_lds_dwordx4 v130, s[20:21]
	s_barrier
	s_waitcnt lgkmcnt(0)
	s_waitcnt lgkmcnt(0)
	v_mfma_f32_16x16x32_bf16 v[60:63], v[142:145], v[158:161], v[60:63]
	v_mfma_f32_16x16x32_bf16 v[60:63], v[146:149], v[162:165], v[60:63]
	v_mfma_f32_16x16x32_bf16 v[44:47], v[142:145], v[166:169], v[44:47]
	v_mfma_f32_16x16x32_bf16 v[44:47], v[146:149], v[170:173], v[44:47]
	v_mfma_f32_16x16x32_bf16 v[28:31], v[142:145], v[174:177], v[28:31]
	v_mfma_f32_16x16x32_bf16 v[28:31], v[146:149], v[178:181], v[28:31]
	v_mfma_f32_16x16x32_bf16 v[12:15], v[142:145], v[208:211], v[12:15]
	v_mfma_f32_16x16x32_bf16 v[12:15], v[146:149], v[212:215], v[12:15]
	v_mfma_f32_16x16x32_bf16 v[4:7], v[150:153], v[208:211], v[4:7]
	v_mfma_f32_16x16x32_bf16 v[4:7], v[154:157], v[212:215], v[4:7]
	v_mfma_f32_16x16x32_bf16 v[20:23], v[150:153], v[174:177], v[20:23]
	v_mfma_f32_16x16x32_bf16 v[20:23], v[154:157], v[178:181], v[20:23]
	v_mfma_f32_16x16x32_bf16 v[36:39], v[150:153], v[166:169], v[36:39]
	v_mfma_f32_16x16x32_bf16 v[36:39], v[154:157], v[170:173], v[36:39]
	v_mfma_f32_16x16x32_bf16 v[52:55], v[150:153], v[158:161], v[52:55]
	v_mfma_f32_16x16x32_bf16 v[52:55], v[154:157], v[162:165], v[52:55]
	s_barrier
	s_add_u32 s40, s18, 0x80000
	s_addc_u32 s41, s19, 0
	s_add_i32 s39, s42, s24
	s_mov_b32 m0, s39
	s_nop 0
	global_load_lds_dwordx4 v184, s[40:41]
	s_add_i32 m0, s39, 0x2000
	s_nop 0
	global_load_lds_dwordx4 v128, s[40:41]
	s_waitcnt vmcnt(6)
	s_barrier
; #define PG8_STAGE(bufoff, gbase, voff) do { _Pragma("unroll") for (int _i = 0; _i < 2; ++_i) \
;         __builtin_amdgcn_global_load_lds((const unsigned*)((const char*)(gbase) + (voff)[_i]), (LAS unsigned*)(lds + (bufoff) + ldsw + _i * 8192), 16, 0, 0); } while (0)
; #define PG8_LDA(dst, b, h) do { _Pragma("unroll") for (int m = 0; m < 4; ++m) _Pragma("unroll") for (int k = 0; k < 2; ++k) dst[m][k] = *(const LAS bf16x8*)(lds + PG8_SA(b, h) + aoff + m * 2048 + k * 1024); } while (0)
; #define PG8_LDB(dst, b, h) do { _Pragma("unroll") for (int n = 0; n < 2; ++n) _Pragma("unroll") for (int k = 0; k < 2; ++k) dst[n][k] = *(const LAS bf16x8*)(lds + PG8_SB(b, h) + boff + n * 2048 + k * 1024); } while (0)
; #define PG8_MMA(ai, bj, At, Bt) do { __builtin_amdgcn_s_setprio(1); _Pragma("unroll") for (int m = 0; m < 4; ++m) _Pragma("unroll") for (int n = 0; n < 2; ++n) _Pragma("unroll") for (int k = 0; k < 2; ++k) \
;         acc[ai][bj][m][n] = __builtin_amdgcn_mfma_f32_16x16x32_bf16(Bt[n][k], At[m][k], acc[ai][bj][m][n], 0, 0, 0); __builtin_amdgcn_s_setprio(0); } while (0)
; #define PG8_WAIT_V(n) asm volatile("s_waitcnt vmcnt(" #n ")" ::: "memory")
; #define PG8_WAIT_L(n) asm volatile("s_waitcnt lgkmcnt(" #n ")" ::: "memory")
; #define PG8_BAR __builtin_amdgcn_s_barrier()
; #define PG8_SCHED __builtin_amdgcn_sched_barrier(0)
; template <class Epi>
; __device__ __forceinline__ void gemm_phase(LAS unsigned char* lds, const Gemm g, const StaticOrder& S, const Epi& E) {
;     ...
;             PG8_WAIT_V(6); PG8_BAR; PG8_MMA(1, 1, At, B1); PG8_BAR;
;             PG8_LDB(B0, 1, 0); PG8_SCHED; PG8_LDA(At, 1, 0); PG8_STAGE(PG8_SA(0, 1), a2 + hstep, voffA);
;             PG8_WAIT_L(8); PG8_BAR; PG8_WAIT_L(0); PG8_MMA(0, 0, At, B0); PG8_BAR; PG8_SCHED;
;             PG8_LDB(B1, 1, 1); PG8_STAGE(PG8_SB(1, 0), b3, voffB);
;             PG8_BAR; PG8_WAIT_L(0); PG8_MMA(0, 1, At, B1); PG8_BAR;
;             PG8_LDA(At, 1, 1); PG8_STAGE(PG8_SA(1, 0), a3, voffA);
	v_mfma_f32_16x16x32_bf16 v[56:59], v[216:219], v[158:161], v[56:59]
	v_mfma_f32_16x16x32_bf16 v[56:59], v[220:223], v[162:165], v[56:59]
	v_mfma_f32_16x16x32_bf16 v[40:43], v[216:219], v[166:169], v[40:43]
	v_mfma_f32_16x16x32_bf16 v[40:43], v[220:223], v[170:173], v[40:43]
	v_mfma_f32_16x16x32_bf16 v[24:27], v[216:219], v[174:177], v[24:27]
	v_mfma_f32_16x16x32_bf16 v[24:27], v[220:223], v[178:181], v[24:27]
	v_mfma_f32_16x16x32_bf16 v[8:11], v[216:219], v[208:211], v[8:11]
	v_mfma_f32_16x16x32_bf16 v[8:11], v[220:223], v[212:215], v[8:11]
	v_mfma_f32_16x16x32_bf16 v[0:3], v[224:227], v[208:211], v[0:3]
	v_mfma_f32_16x16x32_bf16 v[0:3], v[228:231], v[212:215], v[0:3]
	v_mfma_f32_16x16x32_bf16 v[16:19], v[224:227], v[174:177], v[16:19]
	v_mfma_f32_16x16x32_bf16 v[16:19], v[228:231], v[178:181], v[16:19]
	v_mfma_f32_16x16x32_bf16 v[32:35], v[224:227], v[166:169], v[32:35]
	v_mfma_f32_16x16x32_bf16 v[32:35], v[228:231], v[170:173], v[32:35]
	v_mfma_f32_16x16x32_bf16 v[48:51], v[224:227], v[158:161], v[48:51]
	v_mfma_f32_16x16x32_bf16 v[48:51], v[228:231], v[162:165], v[48:51]
	s_add_i32 s39, 0, 0x18000
	v_add_u32_e32 v154, s39, v139
	s_barrier
	ds_read_b128 v[142:145], v154
	ds_read_b128 v[146:149], v154 offset:1024
	ds_read_b128 v[150:153], v154 offset:2048
	ds_read_b128 v[154:157], v154 offset:3072
	s_add_u32 s20, s20, 0x80000
	s_addc_u32 s21, s21, 0
	s_mov_b32 m0, s27
	ds_read_b128 v[158:161], v141 offset:32768
	ds_read_b128 v[162:165], v141 offset:33792
	ds_read_b128 v[166:169], v141 offset:34816
	ds_read_b128 v[170:173], v141 offset:35840
	ds_read_b128 v[174:177], v141 offset:36864
	ds_read_b128 v[178:181], v141 offset:37888
	ds_read_b128 v[208:211], v141 offset:38912
	ds_read_b128 v[212:215], v141 offset:39936
	global_load_lds_dwordx4 v132, s[20:21]
	s_mov_b32 m0, s28
	s_nop 0
	global_load_lds_dwordx4 v130, s[20:21]
	s_waitcnt lgkmcnt(8)
	s_barrier
	s_waitcnt lgkmcnt(0)
	s_waitcnt lgkmcnt(0)
	v_mfma_f32_16x16x32_bf16 v[124:127], v[142:145], v[158:161], v[124:127]
	v_mfma_f32_16x16x32_bf16 v[124:127], v[146:149], v[162:165], v[124:127]
	v_mfma_f32_16x16x32_bf16 v[108:111], v[142:145], v[166:169], v[108:111]
	v_mfma_f32_16x16x32_bf16 v[108:111], v[146:149], v[170:173], v[108:111]
	v_mfma_f32_16x16x32_bf16 v[92:95], v[142:145], v[174:177], v[92:95]
	v_mfma_f32_16x16x32_bf16 v[92:95], v[146:149], v[178:181], v[92:95]
	v_mfma_f32_16x16x32_bf16 v[76:79], v[142:145], v[208:211], v[76:79]
	v_mfma_f32_16x16x32_bf16 v[76:79], v[146:149], v[212:215], v[76:79]
	v_mfma_f32_16x16x32_bf16 v[68:71], v[150:153], v[208:211], v[68:71]
	v_mfma_f32_16x16x32_bf16 v[68:71], v[154:157], v[212:215], v[68:71]
	v_mfma_f32_16x16x32_bf16 v[84:87], v[150:153], v[174:177], v[84:87]
	v_mfma_f32_16x16x32_bf16 v[84:87], v[154:157], v[178:181], v[84:87]
	v_mfma_f32_16x16x32_bf16 v[100:103], v[150:153], v[166:169], v[100:103]
	v_mfma_f32_16x16x32_bf16 v[100:103], v[154:157], v[170:173], v[100:103]
	v_mfma_f32_16x16x32_bf16 v[116:119], v[150:153], v[158:161], v[116:119]
	v_mfma_f32_16x16x32_bf16 v[116:119], v[154:157], v[162:165], v[116:119]
	s_barrier
	s_add_i32 s20, 0, 0x1c000
	s_add_i32 s21, s39, s24
	v_add_u32_e32 v187, s20, v139
	s_mov_b32 m0, s21
	ds_read_b128 v[216:219], v187
	ds_read_b128 v[220:223], v187 offset:1024
	ds_read_b128 v[224:227], v187 offset:2048
	ds_read_b128 v[228:231], v187 offset:3072
	global_load_lds_dwordx4 v184, s[98:99]
	s_add_i32 m0, s21, 0x2000
	s_nop 0
	global_load_lds_dwordx4 v128, s[98:99]
	s_barrier
	s_waitcnt lgkmcnt(0)
	s_waitcnt lgkmcnt(0)
	v_mfma_f32_16x16x32_bf16 v[120:123], v[216:219], v[158:161], v[120:123]
	v_mfma_f32_16x16x32_bf16 v[120:123], v[220:223], v[162:165], v[120:123]
	v_mfma_f32_16x16x32_bf16 v[104:107], v[216:219], v[166:169], v[104:107]
	v_mfma_f32_16x16x32_bf16 v[104:107], v[220:223], v[170:173], v[104:107]
	v_mfma_f32_16x16x32_bf16 v[88:91], v[216:219], v[174:177], v[88:91]
	v_mfma_f32_16x16x32_bf16 v[88:91], v[220:223], v[178:181], v[88:91]
	v_mfma_f32_16x16x32_bf16 v[72:75], v[216:219], v[208:211], v[72:75]
	v_mfma_f32_16x16x32_bf16 v[72:75], v[220:223], v[212:215], v[72:75]
	v_mfma_f32_16x16x32_bf16 v[64:67], v[224:227], v[208:211], v[64:67]
	v_mfma_f32_16x16x32_bf16 v[64:67], v[228:231], v[212:215], v[64:67]
	v_mfma_f32_16x16x32_bf16 v[80:83], v[224:227], v[174:177], v[80:83]
	v_mfma_f32_16x16x32_bf16 v[80:83], v[228:231], v[178:181], v[80:83]
	v_mfma_f32_16x16x32_bf16 v[96:99], v[224:227], v[166:169], v[96:99]
	v_mfma_f32_16x16x32_bf16 v[96:99], v[228:231], v[170:173], v[96:99]
	v_mfma_f32_16x16x32_bf16 v[112:115], v[224:227], v[158:161], v[112:115]
	v_mfma_f32_16x16x32_bf16 v[112:115], v[228:231], v[162:165], v[112:115]
	s_mov_b32 m0, s29
	s_barrier
	ds_read_b128 v[158:161], v141 offset:49152
	ds_read_b128 v[162:165], v141 offset:50176
	ds_read_b128 v[166:169], v141 offset:51200
	ds_read_b128 v[170:173], v141 offset:52224
	ds_read_b128 v[174:177], v141 offset:53248
	ds_read_b128 v[178:181], v141 offset:54272
	ds_read_b128 v[208:211], v141 offset:55296
	ds_read_b128 v[212:215], v141 offset:56320
	global_load_lds_dwordx4 v132, s[100:101]
	s_mov_b32 m0, s30
	s_nop 0
	global_load_lds_dwordx4 v130, s[100:101]
	s_barrier
; __device__ __forceinline__ unsigned pk2(float lo, float hi) { unsigned r; asm("v_cvt_pk_bf16_f32 %0, %1, %2" : "=v"(r) : "v"(lo), "v"(hi)); return r; }
; __device__ __forceinline__ float sigmoidf_(float x) { return __builtin_amdgcn_rcpf(1.0f + __builtin_amdgcn_exp2f(-1.4426950408889634f * x)); }
; #define PG8_STAGE(bufoff, gbase, voff) do { _Pragma("unroll") for (int _i = 0; _i < 2; ++_i) \
;         __builtin_amdgcn_global_load_lds((const unsigned*)((const char*)(gbase) + (voff)[_i]), (LAS unsigned*)(lds + (bufoff) + ldsw + _i * 8192), 16, 0, 0); } while (0)
; #define PG8_MMA(ai, bj, At, Bt) do { __builtin_amdgcn_s_setprio(1); _Pragma("unroll") for (int m = 0; m < 4; ++m) _Pragma("unroll") for (int n = 0; n < 2; ++n) _Pragma("unroll") for (int k = 0; k < 2; ++k) \
;         acc[ai][bj][m][n] = __builtin_amdgcn_mfma_f32_16x16x32_bf16(Bt[n][k], At[m][k], acc[ai][bj][m][n], 0, 0, 0); __builtin_amdgcn_s_setprio(0); } while (0)
; #define PG8_WAIT_V(n) asm volatile("s_waitcnt vmcnt(" #n ")" ::: "memory")
; #define PG8_WAIT_L(n) asm volatile("s_waitcnt lgkmcnt(" #n ")" ::: "memory")
; #define PG8_BAR __builtin_amdgcn_s_barrier()
; #define PG8_SCHED __builtin_amdgcn_sched_barrier(0)
; template <class Epi>
; __device__ __forceinline__ void gemm_phase(LAS unsigned char* lds, const Gemm g, const StaticOrder& S, const Epi& E) {
;     ...
;             PG8_BAR; PG8_WAIT_L(0); PG8_MMA(1, 0, At, B0); PG8_BAR; PG8_SCHED;
;             PG8_STAGE(PG8_SB(1, 1), b3 + hstep, voffB);
;             PG8_WAIT_V(6); PG8_BAR; PG8_MMA(1, 1, At, B1); PG8_BAR;
;     __device__ __forceinline__ void operator()(const Acc& acc, const Unit& u, int wr, int wc, int fr, int fq) const {
;         const int row0 = u.pm * 256 + wr * 64 + fr, col0 = u.pn * 128 + wc * 32 + 8 * fq;
; #pragma unroll
;         for (int ai = 0; ai < 2; ++ai)
; #pragma unroll
;             for (int m = 0; m < 4; ++m) {
;                 float h[8];
; #pragma unroll
;                 for (int n = 0; n < 2; ++n)
; #pragma unroll
;                     for (int j = 0; j < 4; ++j) { const float gv = acc[ai][0][m][n][j], uv = acc[ai][1][m][n][j]; h[n * 4 + j] = gv * sigmoidf_(gv) * uv; }
;                 u32x4 w; w.x = pk2(h[0], h[1]); w.y = pk2(h[2], h[3]); w.z = pk2(h[4], h[5]); w.w = pk2(h[6], h[7]);
;                 *(u32x4*)(H + (size_t)(row0 + ai * 128 + m * 16) * DFF + col0) = w;
	s_waitcnt lgkmcnt(0)
	s_waitcnt lgkmcnt(0)
	v_mfma_f32_16x16x32_bf16 v[60:63], v[142:145], v[158:161], v[60:63]
	v_mfma_f32_16x16x32_bf16 v[60:63], v[146:149], v[162:165], v[60:63]
	v_mfma_f32_16x16x32_bf16 v[44:47], v[142:145], v[166:169], v[44:47]
	v_mfma_f32_16x16x32_bf16 v[44:47], v[146:149], v[170:173], v[44:47]
	v_mfma_f32_16x16x32_bf16 v[28:31], v[142:145], v[174:177], v[28:31]
	v_mfma_f32_16x16x32_bf16 v[28:31], v[146:149], v[178:181], v[28:31]
	v_mfma_f32_16x16x32_bf16 v[12:15], v[142:145], v[208:211], v[12:15]
	v_mfma_f32_16x16x32_bf16 v[12:15], v[146:149], v[212:215], v[12:15]
	v_mfma_f32_16x16x32_bf16 v[4:7], v[150:153], v[208:211], v[4:7]
	v_mfma_f32_16x16x32_bf16 v[4:7], v[154:157], v[212:215], v[4:7]
	v_mfma_f32_16x16x32_bf16 v[20:23], v[150:153], v[174:177], v[20:23]
	v_mfma_f32_16x16x32_bf16 v[20:23], v[154:157], v[178:181], v[20:23]
	v_mfma_f32_16x16x32_bf16 v[36:39], v[150:153], v[166:169], v[36:39]
	v_mfma_f32_16x16x32_bf16 v[36:39], v[154:157], v[170:173], v[36:39]
	v_mfma_f32_16x16x32_bf16 v[52:55], v[150:153], v[158:161], v[52:55]
	v_mfma_f32_16x16x32_bf16 v[52:55], v[154:157], v[162:165], v[52:55]
	s_barrier
	s_add_u32 s18, s18, 0x80080
	s_addc_u32 s19, s19, 0
	s_add_i32 s20, s20, s24
	s_mov_b32 m0, s20
	s_nop 0
	global_load_lds_dwordx4 v184, s[18:19]
	s_add_i32 m0, s20, 0x2000
	s_nop 0
	global_load_lds_dwordx4 v128, s[18:19]
	s_waitcnt vmcnt(6)
	s_barrier
	v_mfma_f32_16x16x32_bf16 v[56:59], v[216:219], v[158:161], v[56:59]
	v_mfma_f32_16x16x32_bf16 v[56:59], v[220:223], v[162:165], v[56:59]
	v_mfma_f32_16x16x32_bf16 v[40:43], v[216:219], v[166:169], v[40:43]
	v_mfma_f32_16x16x32_bf16 v[40:43], v[220:223], v[170:173], v[40:43]
	v_mfma_f32_16x16x32_bf16 v[24:27], v[216:219], v[174:177], v[24:27]
	v_mfma_f32_16x16x32_bf16 v[24:27], v[220:223], v[178:181], v[24:27]
	v_mfma_f32_16x16x32_bf16 v[8:11], v[216:219], v[208:211], v[8:11]
	v_mfma_f32_16x16x32_bf16 v[8:11], v[220:223], v[212:215], v[8:11]
	v_mfma_f32_16x16x32_bf16 v[0:3], v[224:227], v[208:211], v[0:3]
	v_mfma_f32_16x16x32_bf16 v[0:3], v[228:231], v[212:215], v[0:3]
	v_mfma_f32_16x16x32_bf16 v[16:19], v[224:227], v[174:177], v[16:19]
	v_mfma_f32_16x16x32_bf16 v[16:19], v[228:231], v[178:181], v[16:19]
	v_mfma_f32_16x16x32_bf16 v[32:35], v[224:227], v[166:169], v[32:35]
	v_mfma_f32_16x16x32_bf16 v[32:35], v[228:231], v[170:173], v[32:35]
	v_mfma_f32_16x16x32_bf16 v[48:51], v[224:227], v[158:161], v[48:51]
	v_mfma_f32_16x16x32_bf16 v[48:51], v[228:231], v[162:165], v[48:51]
	s_add_i32 s38, s38, 2
	s_add_u32 s16, s16, 0x100
	s_addc_u32 s17, s17, 0
	s_add_u32 s36, s36, 0x100
	s_addc_u32 s37, s37, 0
	s_cmp_gt_u32 s38, 29
	s_barrier
	s_cbranch_scc0 .LBB0_721
	v_mul_f32_e32 v143, 0xbfb8aa3b, v124
	v_exp_f32_e32 v143, v143
	v_lshl_or_b32 v144, s3, 7, v140
	v_lshl_add_u32 v142, s14, 8, v138
	v_ashrrev_i32_e32 v145, 31, v144
	v_add_f32_e32 v143, 1.0, v143
	v_rcp_f32_e32 v143, v143
	s_movk_i32 s1, 0x2c00
	s_and_b64 vcc, exec, s[6:7]
	s_mov_b32 s3, s0
	v_mul_f32_e32 v124, v124, v143
	v_mul_f32_e32 v120, v124, v120
	v_mul_f32_e32 v124, 0xbfb8aa3b, v125
	v_exp_f32_e32 v124, v124
	s_mov_b32 s14, s8
	s_mov_b64 s[18:19], s[12:13]
	v_add_f32_e32 v124, 1.0, v124
	v_rcp_f32_e32 v124, v124
	s_nop 0
	v_mul_f32_e32 v124, v125, v124
	v_mul_f32_e32 v121, v124, v121
	v_mul_f32_e32 v124, 0xbfb8aa3b, v126
	v_exp_f32_e32 v124, v124
	s_nop 0
	v_add_f32_e32 v124, 1.0, v124
	v_rcp_f32_e32 v124, v124
	s_nop 0
	v_mul_f32_e32 v124, v126, v124
	v_mul_f32_e32 v122, v124, v122
	v_mul_f32_e32 v124, 0xbfb8aa3b, v127
	v_exp_f32_e32 v124, v124
	s_nop 0
	v_add_f32_e32 v124, 1.0, v124
	v_rcp_f32_e32 v124, v124
	s_nop 0
	v_mul_f32_e32 v124, v127, v124
	v_mul_f32_e32 v123, v124, v123
	v_mul_f32_e32 v124, 0xbfb8aa3b, v116
	v_exp_f32_e32 v124, v124
	s_nop 0
	v_add_f32_e32 v124, 1.0, v124
	v_rcp_f32_e32 v124, v124
	s_nop 0
	v_mul_f32_e32 v116, v116, v124
	v_mul_f32_e32 v112, v116, v112
	v_mul_f32_e32 v116, 0xbfb8aa3b, v117
	v_exp_f32_e32 v116, v116
	s_nop 0
	v_add_f32_e32 v116, 1.0, v116
	v_rcp_f32_e32 v116, v116
	s_nop 0
	v_mul_f32_e32 v116, v117, v116
	v_mul_f32_e32 v113, v116, v113
	v_mul_f32_e32 v116, 0xbfb8aa3b, v118
	v_exp_f32_e32 v116, v116
	v_cvt_pk_bf16_f32 v117, v122, v123
	s_nop 0
	v_add_f32_e32 v116, 1.0, v116
	v_rcp_f32_e32 v116, v116
	s_nop 0
	v_mul_f32_e32 v116, v118, v116
	v_mul_f32_e32 v114, v116, v114
	v_mul_f32_e32 v116, 0xbfb8aa3b, v119
	v_exp_f32_e32 v116, v116
	v_cvt_pk_bf16_f32 v118, v112, v113
	v_mov_b64_e32 v[112:113], s[66:67]
	v_add_f32_e32 v116, 1.0, v116
	v_rcp_f32_e32 v116, v116
	s_nop 0
	v_mul_f32_e32 v116, v119, v116
	v_mul_f32_e32 v115, v116, v115
	v_cvt_pk_bf16_f32 v116, v120, v121
	v_cvt_pk_bf16_f32 v119, v114, v115
	v_mad_i64_i32 v[120:121], s[16:17], v142, s1, v[112:113]
	v_lshlrev_b64 v[114:115], 1, v[144:145]
	v_lshl_add_u64 v[120:121], v[120:121], 0, v[114:115]
	global_store_dwordx4 v[120:121], v[116:119], off
	s_nop 1
	v_mul_f32_e32 v116, 0xbfb8aa3b, v108
	v_exp_f32_e32 v116, v116
	s_nop 0
	v_add_f32_e32 v116, 1.0, v116
	v_rcp_f32_e32 v116, v116
	s_nop 0
	v_mul_f32_e32 v108, v108, v116
	v_mul_f32_e32 v104, v108, v104
	v_mul_f32_e32 v108, 0xbfb8aa3b, v109
	v_exp_f32_e32 v108, v108
	s_nop 0
	v_add_f32_e32 v108, 1.0, v108
	v_rcp_f32_e32 v108, v108
	s_nop 0
	v_mul_f32_e32 v108, v109, v108
	v_mul_f32_e32 v105, v108, v105
	v_mul_f32_e32 v108, 0xbfb8aa3b, v110
	v_exp_f32_e32 v108, v108
	s_nop 0
	v_add_f32_e32 v108, 1.0, v108
	v_rcp_f32_e32 v108, v108
	s_nop 0
	v_mul_f32_e32 v108, v110, v108
	v_mul_f32_e32 v106, v108, v106
	v_mul_f32_e32 v108, 0xbfb8aa3b, v111
	v_exp_f32_e32 v108, v108
	s_nop 0
	v_add_f32_e32 v108, 1.0, v108
	v_rcp_f32_e32 v108, v108
	s_nop 0
; __device__ __forceinline__ unsigned pk2(float lo, float hi) { unsigned r; asm("v_cvt_pk_bf16_f32 %0, %1, %2" : "=v"(r) : "v"(lo), "v"(hi)); return r; }
; __device__ __forceinline__ float sigmoidf_(float x) { return __builtin_amdgcn_rcpf(1.0f + __builtin_amdgcn_exp2f(-1.4426950408889634f * x)); }
;     __device__ __forceinline__ void operator()(const Acc& acc, const Unit& u, int wr, int wc, int fr, int fq) const {
;     ...
;             for (int m = 0; m < 4; ++m) {
;                 float h[8];
; #pragma unroll
;                 for (int n = 0; n < 2; ++n)
; #pragma unroll
;                     for (int j = 0; j < 4; ++j) { const float gv = acc[ai][0][m][n][j], uv = acc[ai][1][m][n][j]; h[n * 4 + j] = gv * sigmoidf_(gv) * uv; }
;                 u32x4 w; w.x = pk2(h[0], h[1]); w.y = pk2(h[2], h[3]); w.z = pk2(h[4], h[5]); w.w = pk2(h[6], h[7]);
;                 *(u32x4*)(H + (size_t)(row0 + ai * 128 + m * 16) * DFF + col0) = w;
	v_mul_f32_e32 v108, v111, v108
	v_mul_f32_e32 v107, v108, v107
	v_mul_f32_e32 v108, 0xbfb8aa3b, v100
	v_exp_f32_e32 v108, v108
	s_nop 0
	v_add_f32_e32 v108, 1.0, v108
	v_rcp_f32_e32 v108, v108
	s_nop 0
	v_mul_f32_e32 v100, v100, v108
	v_mul_f32_e32 v100, v100, v96
	v_mul_f32_e32 v96, 0xbfb8aa3b, v101
	v_exp_f32_e32 v96, v96
	s_nop 0
	v_add_f32_e32 v96, 1.0, v96
	v_rcp_f32_e32 v96, v96
	s_nop 0
	v_mul_f32_e32 v96, v101, v96
	v_mul_f32_e32 v101, v96, v97
	v_mul_f32_e32 v96, 0xbfb8aa3b, v102
	v_exp_f32_e32 v96, v96
	v_cvt_pk_bf16_f32 v97, v106, v107
	s_nop 0
	v_add_f32_e32 v96, 1.0, v96
	v_rcp_f32_e32 v96, v96
	s_nop 0
	v_mul_f32_e32 v96, v102, v96
	v_mul_f32_e32 v102, v96, v98
	v_mul_f32_e32 v96, 0xbfb8aa3b, v103
	v_exp_f32_e32 v96, v96
	v_cvt_pk_bf16_f32 v98, v100, v101
	v_or_b32_e32 v100, 16, v142
	v_mad_i64_i32 v[100:101], s[16:17], v100, s1, v[112:113]
	v_add_f32_e32 v96, 1.0, v96
	v_rcp_f32_e32 v96, v96
	v_lshl_add_u64 v[100:101], v[100:101], 0, v[114:115]
	v_mul_f32_e32 v96, v103, v96
	v_mul_f32_e32 v99, v96, v99
	v_cvt_pk_bf16_f32 v96, v104, v105
	v_cvt_pk_bf16_f32 v99, v102, v99
	global_store_dwordx4 v[100:101], v[96:99], off
	s_nop 1
	v_mul_f32_e32 v96, 0xbfb8aa3b, v92
	v_exp_f32_e32 v96, v96
	s_nop 0
	v_add_f32_e32 v96, 1.0, v96
	v_rcp_f32_e32 v96, v96
	s_nop 0
	v_mul_f32_e32 v92, v92, v96
	v_mul_f32_e32 v88, v92, v88
	v_mul_f32_e32 v92, 0xbfb8aa3b, v93
	v_exp_f32_e32 v92, v92
	s_nop 0
	v_add_f32_e32 v92, 1.0, v92
	v_rcp_f32_e32 v92, v92
	s_nop 0
	v_mul_f32_e32 v92, v93, v92
	v_mul_f32_e32 v89, v92, v89
	v_mul_f32_e32 v92, 0xbfb8aa3b, v94
	v_exp_f32_e32 v92, v92
	s_nop 0
	v_add_f32_e32 v92, 1.0, v92
	v_rcp_f32_e32 v92, v92
	s_nop 0
	v_mul_f32_e32 v92, v94, v92
	v_mul_f32_e32 v90, v92, v90
	v_mul_f32_e32 v92, 0xbfb8aa3b, v95
	v_exp_f32_e32 v92, v92
	s_nop 0
	v_add_f32_e32 v92, 1.0, v92
	v_rcp_f32_e32 v92, v92
	s_nop 0
	v_mul_f32_e32 v92, v95, v92
	v_mul_f32_e32 v91, v92, v91
	v_mul_f32_e32 v92, 0xbfb8aa3b, v84
	v_exp_f32_e32 v92, v92
	s_nop 0
	v_add_f32_e32 v92, 1.0, v92
	v_rcp_f32_e32 v92, v92
	s_nop 0
	v_mul_f32_e32 v84, v84, v92
	v_mul_f32_e32 v84, v84, v80
	v_mul_f32_e32 v80, 0xbfb8aa3b, v85
	v_exp_f32_e32 v80, v80
	s_nop 0
	v_add_f32_e32 v80, 1.0, v80
	v_rcp_f32_e32 v80, v80
	s_nop 0
	v_mul_f32_e32 v80, v85, v80
	v_mul_f32_e32 v85, v80, v81
	v_mul_f32_e32 v80, 0xbfb8aa3b, v86
	v_exp_f32_e32 v80, v80
	v_cvt_pk_bf16_f32 v81, v90, v91
	s_nop 0
	v_add_f32_e32 v80, 1.0, v80
	v_rcp_f32_e32 v80, v80
	s_nop 0
	v_mul_f32_e32 v80, v86, v80
	v_mul_f32_e32 v86, v80, v82
	v_mul_f32_e32 v80, 0xbfb8aa3b, v87
	v_exp_f32_e32 v80, v80
	v_cvt_pk_bf16_f32 v82, v84, v85
	v_or_b32_e32 v84, 32, v142
	v_mad_i64_i32 v[84:85], s[16:17], v84, s1, v[112:113]
	v_add_f32_e32 v80, 1.0, v80
	v_rcp_f32_e32 v80, v80
	v_lshl_add_u64 v[84:85], v[84:85], 0, v[114:115]
	v_mul_f32_e32 v80, v87, v80
	v_mul_f32_e32 v83, v80, v83
	v_cvt_pk_bf16_f32 v80, v88, v89
	v_cvt_pk_bf16_f32 v83, v86, v83
	global_store_dwordx4 v[84:85], v[80:83], off
	s_nop 1
	v_mul_f32_e32 v80, 0xbfb8aa3b, v76
	v_exp_f32_e32 v80, v80
	s_nop 0
	v_add_f32_e32 v80, 1.0, v80
	v_rcp_f32_e32 v80, v80
	s_nop 0
	v_mul_f32_e32 v76, v76, v80
	v_mul_f32_e32 v72, v76, v72
	v_mul_f32_e32 v76, 0xbfb8aa3b, v77
	v_exp_f32_e32 v76, v76
	s_nop 0
	v_add_f32_e32 v76, 1.0, v76
	v_rcp_f32_e32 v76, v76
	s_nop 0
	v_mul_f32_e32 v76, v77, v76
	v_mul_f32_e32 v73, v76, v73
	v_mul_f32_e32 v76, 0xbfb8aa3b, v78
	v_exp_f32_e32 v76, v76
	s_nop 0
	v_add_f32_e32 v76, 1.0, v76
	v_rcp_f32_e32 v76, v76
	s_nop 0
	v_mul_f32_e32 v76, v78, v76
	v_mul_f32_e32 v74, v76, v74
	v_mul_f32_e32 v76, 0xbfb8aa3b, v79
	v_exp_f32_e32 v76, v76
	s_nop 0
	v_add_f32_e32 v76, 1.0, v76
	v_rcp_f32_e32 v76, v76
	s_nop 0
	v_mul_f32_e32 v76, v79, v76
	v_mul_f32_e32 v75, v76, v75
	v_mul_f32_e32 v76, 0xbfb8aa3b, v68
	v_exp_f32_e32 v76, v76
	s_nop 0
	v_add_f32_e32 v76, 1.0, v76
	v_rcp_f32_e32 v76, v76
	s_nop 0
	v_mul_f32_e32 v68, v68, v76
	v_mul_f32_e32 v68, v68, v64
	v_mul_f32_e32 v64, 0xbfb8aa3b, v69
	v_exp_f32_e32 v64, v64
	s_nop 0
	v_add_f32_e32 v64, 1.0, v64
	v_rcp_f32_e32 v64, v64
	s_nop 0
	v_mul_f32_e32 v64, v69, v64
	v_mul_f32_e32 v69, v64, v65
	v_mul_f32_e32 v64, 0xbfb8aa3b, v70
	v_exp_f32_e32 v64, v64
	v_cvt_pk_bf16_f32 v65, v74, v75
	s_nop 0
	v_add_f32_e32 v64, 1.0, v64
	v_rcp_f32_e32 v64, v64
	s_nop 0
	v_mul_f32_e32 v64, v70, v64
	v_mul_f32_e32 v70, v64, v66
	v_mul_f32_e32 v64, 0xbfb8aa3b, v71
	v_exp_f32_e32 v64, v64
	v_cvt_pk_bf16_f32 v66, v68, v69
	v_or_b32_e32 v68, 48, v142
	v_mad_i64_i32 v[68:69], s[16:17], v68, s1, v[112:113]
	v_add_f32_e32 v64, 1.0, v64
	v_rcp_f32_e32 v64, v64
	v_lshl_add_u64 v[68:69], v[68:69], 0, v[114:115]
	v_mul_f32_e32 v64, v71, v64
	v_mul_f32_e32 v67, v64, v67
	v_cvt_pk_bf16_f32 v64, v72, v73
	v_cvt_pk_bf16_f32 v67, v70, v67
	global_store_dwordx4 v[68:69], v[64:67], off
	s_nop 1
	v_mul_f32_e32 v65, 0xbfb8aa3b, v60
	v_exp_f32_e32 v65, v65
	v_add_u32_e32 v64, 0x80, v142
	v_add_f32_e32 v65, 1.0, v65
	v_rcp_f32_e32 v65, v65
	s_nop 0
	v_mul_f32_e32 v60, v60, v65
	v_mul_f32_e32 v56, v60, v56
	v_mul_f32_e32 v60, 0xbfb8aa3b, v61
	v_exp_f32_e32 v60, v60
	s_nop 0
	v_add_f32_e32 v60, 1.0, v60
	v_rcp_f32_e32 v60, v60
	s_nop 0
	v_mul_f32_e32 v60, v61, v60
	v_mul_f32_e32 v57, v60, v57
	v_mul_f32_e32 v60, 0xbfb8aa3b, v62
	v_exp_f32_e32 v60, v60
	s_nop 0
	v_add_f32_e32 v60, 1.0, v60
	v_rcp_f32_e32 v60, v60
	s_nop 0
	v_mul_f32_e32 v60, v62, v60
	v_mul_f32_e32 v58, v60, v58
	v_mul_f32_e32 v60, 0xbfb8aa3b, v63
	v_exp_f32_e32 v60, v60
	s_nop 0
	v_add_f32_e32 v60, 1.0, v60
	v_rcp_f32_e32 v60, v60
	s_nop 0
	v_mul_f32_e32 v60, v63, v60
	v_mul_f32_e32 v59, v60, v59
	v_mul_f32_e32 v60, 0xbfb8aa3b, v52
	v_exp_f32_e32 v60, v60
	s_nop 0
; __device__ __forceinline__ unsigned pk2(float lo, float hi) { unsigned r; asm("v_cvt_pk_bf16_f32 %0, %1, %2" : "=v"(r) : "v"(lo), "v"(hi)); return r; }
; __device__ __forceinline__ float sigmoidf_(float x) { return __builtin_amdgcn_rcpf(1.0f + __builtin_amdgcn_exp2f(-1.4426950408889634f * x)); }
; #define PG8_WAIT_V(n) asm volatile("s_waitcnt vmcnt(" #n ")" ::: "memory")
; #define PG8_BAR __builtin_amdgcn_s_barrier()
; template <class Epi>
; __device__ __forceinline__ void gemm_phase(LAS unsigned char* lds, const Gemm g, const StaticOrder& S, const Epi& E) {
;     ...
;         if (!has_next) break;
; #pragma unroll
;         for (int a = 0; a < 2; ++a)
; #pragma unroll
;             for (int b = 0; b < 2; ++b)
; #pragma unroll
;                 for (int m = 0; m < 4; ++m)
; #pragma unroll
;                     for (int n = 0; n < 2; ++n) acc[a][b][m][n] = (f32x4){0.f, 0.f, 0.f, 0.f};
;         cur = nxt; cA = nA; cB = nB; ++ui;
;     }
;     PG8_WAIT_V(0);
;     if (wr == 0) PG8_BAR;
;     PG8_BAR;
;     __device__ __forceinline__ void operator()(const Acc& acc, const Unit& u, int wr, int wc, int fr, int fq) const {
;     ...
;         for (int ai = 0; ai < 2; ++ai)
; #pragma unroll
;             for (int m = 0; m < 4; ++m) {
;                 float h[8];
; #pragma unroll
;                 for (int n = 0; n < 2; ++n)
; #pragma unroll
;                     for (int j = 0; j < 4; ++j) { const float gv = acc[ai][0][m][n][j], uv = acc[ai][1][m][n][j]; h[n * 4 + j] = gv * sigmoidf_(gv) * uv; }
;                 u32x4 w; w.x = pk2(h[0], h[1]); w.y = pk2(h[2], h[3]); w.z = pk2(h[4], h[5]); w.w = pk2(h[6], h[7]);
;                 *(u32x4*)(H + (size_t)(row0 + ai * 128 + m * 16) * DFF + col0) = w;
	v_add_f32_e32 v60, 1.0, v60
	v_rcp_f32_e32 v60, v60
	s_nop 0
	v_mul_f32_e32 v52, v52, v60
	v_mul_f32_e32 v52, v52, v48
	v_mul_f32_e32 v48, 0xbfb8aa3b, v53
	v_exp_f32_e32 v48, v48
	s_nop 0
	v_add_f32_e32 v48, 1.0, v48
	v_rcp_f32_e32 v48, v48
	s_nop 0
	v_mul_f32_e32 v48, v53, v48
	v_mul_f32_e32 v53, v48, v49
	v_mul_f32_e32 v48, 0xbfb8aa3b, v54
	v_exp_f32_e32 v48, v48
	v_cvt_pk_bf16_f32 v49, v58, v59
	s_nop 0
	v_add_f32_e32 v48, 1.0, v48
	v_rcp_f32_e32 v48, v48
	s_nop 0
	v_mul_f32_e32 v48, v54, v48
	v_mul_f32_e32 v54, v48, v50
	v_mul_f32_e32 v48, 0xbfb8aa3b, v55
	v_exp_f32_e32 v48, v48
	v_cvt_pk_bf16_f32 v50, v52, v53
	v_mad_i64_i32 v[52:53], s[16:17], v64, s1, v[112:113]
	v_add_f32_e32 v48, 1.0, v48
	v_rcp_f32_e32 v48, v48
	v_lshl_add_u64 v[52:53], v[52:53], 0, v[114:115]
	v_mul_f32_e32 v48, v55, v48
	v_mul_f32_e32 v51, v48, v51
	v_cvt_pk_bf16_f32 v48, v56, v57
	v_cvt_pk_bf16_f32 v51, v54, v51
	global_store_dwordx4 v[52:53], v[48:51], off
	s_nop 1
	v_mul_f32_e32 v48, 0xbfb8aa3b, v44
	v_exp_f32_e32 v48, v48
	s_nop 0
	v_add_f32_e32 v48, 1.0, v48
	v_rcp_f32_e32 v48, v48
	s_nop 0
	v_mul_f32_e32 v44, v44, v48
	v_mul_f32_e32 v40, v44, v40
	v_mul_f32_e32 v44, 0xbfb8aa3b, v45
	v_exp_f32_e32 v44, v44
	s_nop 0
	v_add_f32_e32 v44, 1.0, v44
	v_rcp_f32_e32 v44, v44
	s_nop 0
	v_mul_f32_e32 v44, v45, v44
	v_mul_f32_e32 v41, v44, v41
	v_mul_f32_e32 v44, 0xbfb8aa3b, v46
	v_exp_f32_e32 v44, v44
	s_nop 0
	v_add_f32_e32 v44, 1.0, v44
	v_rcp_f32_e32 v44, v44
	s_nop 0
	v_mul_f32_e32 v44, v46, v44
	v_mul_f32_e32 v42, v44, v42
	v_mul_f32_e32 v44, 0xbfb8aa3b, v47
	v_exp_f32_e32 v44, v44
	s_nop 0
	v_add_f32_e32 v44, 1.0, v44
	v_rcp_f32_e32 v44, v44
	s_nop 0
	v_mul_f32_e32 v44, v47, v44
	v_mul_f32_e32 v43, v44, v43
	v_mul_f32_e32 v44, 0xbfb8aa3b, v36
	v_exp_f32_e32 v44, v44
	s_nop 0
	v_add_f32_e32 v44, 1.0, v44
	v_rcp_f32_e32 v44, v44
	s_nop 0
	v_mul_f32_e32 v36, v36, v44
	v_mul_f32_e32 v36, v36, v32
	v_mul_f32_e32 v32, 0xbfb8aa3b, v37
	v_exp_f32_e32 v32, v32
	s_nop 0
	v_add_f32_e32 v32, 1.0, v32
	v_rcp_f32_e32 v32, v32
	s_nop 0
	v_mul_f32_e32 v32, v37, v32
	v_mul_f32_e32 v37, v32, v33
	v_mul_f32_e32 v32, 0xbfb8aa3b, v38
	v_exp_f32_e32 v32, v32
	v_cvt_pk_bf16_f32 v33, v42, v43
	s_nop 0
	v_add_f32_e32 v32, 1.0, v32
	v_rcp_f32_e32 v32, v32
	s_nop 0
	v_mul_f32_e32 v32, v38, v32
	v_mul_f32_e32 v38, v32, v34
	v_mul_f32_e32 v32, 0xbfb8aa3b, v39
	v_exp_f32_e32 v32, v32
	v_cvt_pk_bf16_f32 v34, v36, v37
	v_add_u32_e32 v36, 0x90, v142
	v_mad_i64_i32 v[36:37], s[16:17], v36, s1, v[112:113]
	v_add_f32_e32 v32, 1.0, v32
	v_rcp_f32_e32 v32, v32
	v_lshl_add_u64 v[36:37], v[36:37], 0, v[114:115]
	v_mul_f32_e32 v32, v39, v32
	v_mul_f32_e32 v35, v32, v35
	v_cvt_pk_bf16_f32 v32, v40, v41
	v_cvt_pk_bf16_f32 v35, v38, v35
	global_store_dwordx4 v[36:37], v[32:35], off
	s_nop 1
	v_mul_f32_e32 v32, 0xbfb8aa3b, v28
	v_exp_f32_e32 v32, v32
	s_nop 0
	v_add_f32_e32 v32, 1.0, v32
	v_rcp_f32_e32 v32, v32
	s_nop 0
	v_mul_f32_e32 v28, v28, v32
	v_mul_f32_e32 v24, v28, v24
	v_mul_f32_e32 v28, 0xbfb8aa3b, v29
	v_exp_f32_e32 v28, v28
	s_nop 0
	v_add_f32_e32 v28, 1.0, v28
	v_rcp_f32_e32 v28, v28
	s_nop 0
	v_mul_f32_e32 v28, v29, v28
	v_mul_f32_e32 v25, v28, v25
	v_mul_f32_e32 v28, 0xbfb8aa3b, v30
	v_exp_f32_e32 v28, v28
	s_nop 0
	v_add_f32_e32 v28, 1.0, v28
	v_rcp_f32_e32 v28, v28
	s_nop 0
	v_mul_f32_e32 v28, v30, v28
	v_mul_f32_e32 v26, v28, v26
	v_mul_f32_e32 v28, 0xbfb8aa3b, v31
	v_exp_f32_e32 v28, v28
	s_nop 0
	v_add_f32_e32 v28, 1.0, v28
	v_rcp_f32_e32 v28, v28
	s_nop 0
	v_mul_f32_e32 v28, v31, v28
	v_mul_f32_e32 v27, v28, v27
	v_mul_f32_e32 v28, 0xbfb8aa3b, v20
	v_exp_f32_e32 v28, v28
	s_nop 0
	v_add_f32_e32 v28, 1.0, v28
	v_rcp_f32_e32 v28, v28
	s_nop 0
	v_mul_f32_e32 v20, v20, v28
	v_mul_f32_e32 v20, v20, v16
	v_mul_f32_e32 v16, 0xbfb8aa3b, v21
	v_exp_f32_e32 v16, v16
	s_nop 0
	v_add_f32_e32 v16, 1.0, v16
	v_rcp_f32_e32 v16, v16
	s_nop 0
	v_mul_f32_e32 v16, v21, v16
	v_mul_f32_e32 v21, v16, v17
	v_mul_f32_e32 v16, 0xbfb8aa3b, v22
	v_exp_f32_e32 v16, v16
	v_cvt_pk_bf16_f32 v17, v26, v27
	s_nop 0
	v_add_f32_e32 v16, 1.0, v16
	v_rcp_f32_e32 v16, v16
	s_nop 0
	v_mul_f32_e32 v16, v22, v16
	v_mul_f32_e32 v22, v16, v18
	v_mul_f32_e32 v16, 0xbfb8aa3b, v23
	v_exp_f32_e32 v16, v16
	v_cvt_pk_bf16_f32 v18, v20, v21
	v_add_u32_e32 v20, 0xa0, v142
	v_mad_i64_i32 v[20:21], s[16:17], v20, s1, v[112:113]
	v_add_f32_e32 v16, 1.0, v16
	v_rcp_f32_e32 v16, v16
	v_lshl_add_u64 v[20:21], v[20:21], 0, v[114:115]
	v_mul_f32_e32 v16, v23, v16
	v_mul_f32_e32 v19, v16, v19
	v_cvt_pk_bf16_f32 v16, v24, v25
	v_cvt_pk_bf16_f32 v19, v22, v19
	global_store_dwordx4 v[20:21], v[16:19], off
	s_nop 1
	v_mul_f32_e32 v16, 0xbfb8aa3b, v12
	v_exp_f32_e32 v16, v16
	s_nop 0
	v_add_f32_e32 v16, 1.0, v16
	v_rcp_f32_e32 v16, v16
	s_nop 0
	v_mul_f32_e32 v12, v12, v16
	v_mul_f32_e32 v8, v12, v8
	v_mul_f32_e32 v12, 0xbfb8aa3b, v13
	v_exp_f32_e32 v12, v12
	s_nop 0
	v_add_f32_e32 v12, 1.0, v12
	v_rcp_f32_e32 v12, v12
	s_nop 0
	v_mul_f32_e32 v12, v13, v12
	v_mul_f32_e32 v9, v12, v9
	v_mul_f32_e32 v12, 0xbfb8aa3b, v14
	v_exp_f32_e32 v12, v12
	s_nop 0
	v_add_f32_e32 v12, 1.0, v12
	v_rcp_f32_e32 v12, v12
	s_nop 0
	v_mul_f32_e32 v12, v14, v12
	v_mul_f32_e32 v10, v12, v10
	v_mul_f32_e32 v12, 0xbfb8aa3b, v15
	v_exp_f32_e32 v12, v12
	s_nop 0
	v_add_f32_e32 v12, 1.0, v12
	v_rcp_f32_e32 v12, v12
	s_nop 0
	v_mul_f32_e32 v12, v15, v12
	v_mul_f32_e32 v11, v12, v11
	v_mul_f32_e32 v12, 0xbfb8aa3b, v4
	v_exp_f32_e32 v12, v12
	s_nop 0
	v_add_f32_e32 v12, 1.0, v12
	v_rcp_f32_e32 v12, v12
	s_nop 0
	v_mul_f32_e32 v4, v4, v12
	v_mul_f32_e32 v4, v4, v0
	v_mul_f32_e32 v0, 0xbfb8aa3b, v5
	v_exp_f32_e32 v0, v0
	s_nop 0
	v_add_f32_e32 v0, 1.0, v0
	v_rcp_f32_e32 v0, v0
	s_nop 0
	v_mul_f32_e32 v0, v5, v0
	v_mul_f32_e32 v5, v0, v1
	v_mul_f32_e32 v0, 0xbfb8aa3b, v6
	v_exp_f32_e32 v0, v0
	v_cvt_pk_bf16_f32 v1, v10, v11
	s_nop 0
	v_add_f32_e32 v0, 1.0, v0
	v_rcp_f32_e32 v0, v0
	s_nop 0
	v_mul_f32_e32 v0, v6, v0
	v_mul_f32_e32 v6, v0, v2
	v_mul_f32_e32 v0, 0xbfb8aa3b, v7
	v_exp_f32_e32 v0, v0
	v_cvt_pk_bf16_f32 v2, v4, v5
	v_add_u32_e32 v4, 0xb0, v142
	v_mad_i64_i32 v[4:5], s[16:17], v4, s1, v[112:113]
	v_add_f32_e32 v0, 1.0, v0
	v_rcp_f32_e32 v0, v0
	v_lshl_add_u64 v[4:5], v[4:5], 0, v[114:115]
	s_mov_b64 s[16:17], s[10:11]
	v_mul_f32_e32 v0, v7, v0
	v_mul_f32_e32 v3, v0, v3
	v_cvt_pk_bf16_f32 v0, v8, v9
	v_cvt_pk_bf16_f32 v3, v6, v3
	global_store_dwordx4 v[4:5], v[0:3], off
	s_cbranch_vccz .LBB0_718
	s_waitcnt vmcnt(0)
	s_cmpk_gt_u32 s23, 0xff
	s_cbranch_scc1 .LBB0_725
	s_barrier

; #define LAS __attribute__((address_space(3)))
; __device__ __forceinline__ void xcd_barrier_post(unsigned* bar) { if (threadIdx.x == 0) (void)xb_add(&bar[XB_XCNT(xb_xcc_id())], 1u); }
; __global__ void __launch_bounds__(512, 2) mega(Params p) {
;     extern __shared__ __attribute__((aligned(16))) unsigned char shm[];
;     cg::grid_group grid = cg::this_grid();
;     unsigned* bar = (unsigned*)(p.ws + OFF_BAR);
;     volatile LAS unsigned* bst = (volatile LAS unsigned*)((LAS unsigned char*)shm + LDS_BYTES - 16);
;     if (threadIdx.x == 0) { bst[0] = 0u; bst[1] = 0u; }
;     __syncthreads();
;     xcd_barrier_post(bar);
	.amdhsa_kernel _Z4mega6Params
		.amdhsa_group_segment_fixed_size 0
		.amdhsa_private_segment_fixed_size 0
		.amdhsa_kernarg_size 440
		.amdhsa_user_sgpr_count 2
		.amdhsa_user_sgpr_dispatch_ptr 0
		.amdhsa_user_sgpr_queue_ptr 0
		.amdhsa_user_sgpr_kernarg_segment_ptr 1
		.amdhsa_user_sgpr_dispatch_id 0
		.amdhsa_user_sgpr_kernarg_preload_length 0
		.amdhsa_user_sgpr_kernarg_preload_offset 0
		.amdhsa_user_sgpr_private_segment_size 0
		.amdhsa_uses_dynamic_stack 0
		.amdhsa_enable_private_segment 0
		.amdhsa_system_sgpr_workgroup_id_x 1
		.amdhsa_system_sgpr_workgroup_id_y 0
		.amdhsa_system_sgpr_workgroup_id_z 0
		.amdhsa_system_sgpr_workgroup_info 0
		.amdhsa_system_vgpr_workitem_id 2
		.amdhsa_next_free_vgpr 256
		.amdhsa_next_free_sgpr 102
		.amdhsa_accum_offset 256
		.amdhsa_reserve_vcc 1
		.amdhsa_float_round_mode_32 0
		.amdhsa_float_round_mode_16_64 0
		.amdhsa_float_denorm_mode_32 3
		.amdhsa_float_denorm_mode_16_64 3
		.amdhsa_dx10_clamp 1
		.amdhsa_ieee_mode 1
		.amdhsa_fp16_overflow 0
		.amdhsa_tg_split 0
		.amdhsa_exception_fp_ieee_invalid_op 0
		.amdhsa_exception_fp_denorm_src 0
		.amdhsa_exception_fp_ieee_div_zero 0
		.amdhsa_exception_fp_ieee_overflow 0
		.amdhsa_exception_fp_ieee_underflow 0
		.amdhsa_exception_fp_ieee_inexact 0
		.amdhsa_exception_int_div_zero 0
	.end_amdhsa_kernel

; #define LAS __attribute__((address_space(3)))
; __device__ __forceinline__ void xcd_barrier_post(unsigned* bar) { if (threadIdx.x == 0) (void)xb_add(&bar[XB_XCNT(xb_xcc_id())], 1u); }
; __global__ void __launch_bounds__(512, 2) mega(Params p) {
;     extern __shared__ __attribute__((aligned(16))) unsigned char shm[];
;     cg::grid_group grid = cg::this_grid();
;     unsigned* bar = (unsigned*)(p.ws + OFF_BAR);
;     volatile LAS unsigned* bst = (volatile LAS unsigned*)((LAS unsigned char*)shm + LDS_BYTES - 16);
;     if (threadIdx.x == 0) { bst[0] = 0u; bst[1] = 0u; }
;     __syncthreads();
;     xcd_barrier_post(bar);
amdhsa.kernels:
  - .agpr_count:     0
    .args:
      - .offset:         0
        .size:           184
        .value_kind:     by_value
      - .offset:         184
        .size:           4
        .value_kind:     hidden_block_count_x
      - .offset:         188
        .size:           4
        .value_kind:     hidden_block_count_y
      - .offset:         192
        .size:           4
        .value_kind:     hidden_block_count_z
      - .offset:         196
        .size:           2
        .value_kind:     hidden_group_size_x
      - .offset:         198
        .size:           2
        .value_kind:     hidden_group_size_y
      - .offset:         200
        .size:           2
        .value_kind:     hidden_group_size_z
      - .offset:         202
        .size:           2
        .value_kind:     hidden_remainder_x
      - .offset:         204
        .size:           2
        .value_kind:     hidden_remainder_y
      - .offset:         206
        .size:           2
        .value_kind:     hidden_remainder_z
      - .offset:         224
        .size:           8
        .value_kind:     hidden_global_offset_x
      - .offset:         232
        .size:           8
        .value_kind:     hidden_global_offset_y
      - .offset:         240
        .size:           8
        .value_kind:     hidden_global_offset_z
      - .offset:         248
        .size:           2
        .value_kind:     hidden_grid_dims
      - .offset:         272
        .size:           8
        .value_kind:     hidden_multigrid_sync_arg
      - .offset:         304
        .size:           4
        .value_kind:     hidden_dynamic_lds_size
    .group_segment_fixed_size: 0
    .kernarg_segment_align: 8
    .kernarg_segment_size: 440
    .language:       OpenCL C
    .language_version:
      - 2
      - 0
    .max_flat_workgroup_size: 512
    .name:           _Z4mega6Params
    .private_segment_fixed_size: 0
    .sgpr_count:     108
    .sgpr_spill_count: 188
    .symbol:         _Z4mega6Params.kd
    .uniform_work_group_size: 1
    .uses_dynamic_stack: false
    .vgpr_count:     256
    .vgpr_spill_count: 0
    .wavefront_size: 64
